# GEMM: next unit's SA(1,1) stage issued before the epilogue stores; first K-pair of later units waits vmcnt(24) so tile 1 is consumed while stores drain
# baseline (speedup 1.0000x reference)
.LBB0_182:
	s_mov_b32 s99, 0
	s_cmp_lt_i32 s44, 2
	s_cselect_b64 s[8:9], -1, 0
	s_add_u32 s48, s42, 0x4b44000
	s_addc_u32 s49, s43, 0
	s_add_u32 s50, s42, 0x4d44000
	s_addc_u32 s51, s43, 0
	s_and_b64 s[10:11], s[8:9], s[6:7]
	s_andn2_b64 vcc, exec, s[10:11]
	s_cbranch_vccnz .LBB0_355
	s_ashr_i32 s3, s2, 31
	s_cmpk_gt_i32 s2, 0x43f
	s_cselect_b64 s[18:19], -1, 0
	v_readfirstlane_b32 s22, v213
	s_and_b64 vcc, exec, s[18:19]
	s_cbranch_vccz .LBB0_187
	s_add_u32 s16, s2, 0xfffffbc0
	s_addc_u32 s17, s3, -1
	s_cbranch_execz .LBB0_188
	s_andn2_b64 vcc, exec, s[18:19]
	s_cbranch_vccz .LBB0_189

.LBB0_237:
	ds_read_b128 v[156:159], v170
	ds_read_b128 v[176:179], v170 offset:1024
	ds_read_b128 v[180:183], v170 offset:2048
	ds_read_b128 v[184:187], v170 offset:3072
	s_add_u32 s33, s76, 0xfff80080
	s_addc_u32 s80, s77, -1
	s_cmp_eq_u32 s29, 28
	s_cselect_b64 vcc, -1, 0
	s_and_b64 s[78:79], vcc, exec
	s_cselect_b32 s81, s9, s80
	s_cselect_b32 s80, s59, s33
	s_cselect_b32 s79, s61, s28
	s_cselect_b32 s78, s75, s83
	s_and_b64 vcc, s[6:7], vcc
	v_cndmask_b32_e32 v132, v153, v173, vcc
	v_lshl_add_u64 v[154:155], s[76:77], 0, v[136:137]
	s_add_i32 m0, s86, 0xc000
	ds_read_b128 v[188:191], v171
	ds_read_b128 v[192:195], v171 offset:1024
	ds_read_b128 v[196:199], v171 offset:2048
	ds_read_b128 v[200:203], v171 offset:3072
	ds_read_b128 v[204:207], v171 offset:4096
	ds_read_b128 v[208:211], v171 offset:5120
	ds_read_b128 v[214:217], v171 offset:6144
	ds_read_b128 v[218:221], v171 offset:7168
	global_load_lds_dwordx4 v[154:155], off
	v_lshl_add_u64 v[154:155], s[76:77], 0, v[138:139]
	s_add_i32 m0, s86, 0xe000
	s_nop 0
	global_load_lds_dwordx4 v[154:155], off
	s_waitcnt lgkmcnt(8)
	s_barrier
	s_waitcnt lgkmcnt(0)
	v_cndmask_b32_e32 v154, v152, v174, vcc
	s_setprio 1
	s_waitcnt lgkmcnt(0)
	v_mfma_f32_16x16x32_bf16 v[124:127], v[156:159], v[188:191], v[124:127]
	v_mfma_f32_16x16x32_bf16 v[120:123], v[180:183], v[188:191], v[120:123]
	v_mfma_f32_16x16x32_bf16 v[116:119], v[156:159], v[196:199], v[116:119]
	v_mfma_f32_16x16x32_bf16 v[112:115], v[180:183], v[196:199], v[112:115]
	v_mfma_f32_16x16x32_bf16 v[108:111], v[156:159], v[204:207], v[108:111]
	v_mfma_f32_16x16x32_bf16 v[104:107], v[180:183], v[204:207], v[104:107]
	v_mfma_f32_16x16x32_bf16 v[100:103], v[156:159], v[214:217], v[100:103]
	v_mfma_f32_16x16x32_bf16 v[96:99], v[180:183], v[214:217], v[96:99]
	v_mfma_f32_16x16x32_bf16 v[124:127], v[176:179], v[192:195], v[124:127]
	v_mfma_f32_16x16x32_bf16 v[120:123], v[184:187], v[192:195], v[120:123]
	v_mfma_f32_16x16x32_bf16 v[116:119], v[176:179], v[200:203], v[116:119]
	v_mfma_f32_16x16x32_bf16 v[112:115], v[184:187], v[200:203], v[112:115]
	v_mfma_f32_16x16x32_bf16 v[108:111], v[176:179], v[208:211], v[108:111]
	v_mfma_f32_16x16x32_bf16 v[104:107], v[184:187], v[208:211], v[104:107]
	v_mfma_f32_16x16x32_bf16 v[100:103], v[176:179], v[218:221], v[100:103]
	v_mfma_f32_16x16x32_bf16 v[96:99], v[184:187], v[218:221], v[96:99]
	s_setprio 0
	s_barrier
	s_add_i32 s33, s96, s85
	s_mov_b32 m0, s33
	ds_read_b128 v[222:225], v172
	ds_read_b128 v[228:231], v172 offset:1024
	ds_read_b128 v[232:235], v172 offset:2048
	ds_read_b128 v[236:239], v172 offset:3072
	global_load_lds_dwordx4 v132, s[78:79]
	s_add_i32 m0, s33, 0x2000
	v_mov_b32_e32 v155, v133
	global_load_lds_dwordx4 v154, s[78:79]
	s_barrier
	s_waitcnt lgkmcnt(0)
	v_lshl_add_u64 v[160:161], s[78:79], 0, v[132:133]
	v_lshl_add_u64 v[240:241], s[78:79], 0, v[154:155]
	s_setprio 1
	s_waitcnt lgkmcnt(0)
	v_mfma_f32_16x16x32_bf16 v[60:63], v[222:225], v[188:191], v[60:63]
	v_mfma_f32_16x16x32_bf16 v[56:59], v[232:235], v[188:191], v[56:59]
	v_mfma_f32_16x16x32_bf16 v[52:55], v[222:225], v[196:199], v[52:55]
	v_mfma_f32_16x16x32_bf16 v[48:51], v[232:235], v[196:199], v[48:51]
	v_mfma_f32_16x16x32_bf16 v[44:47], v[222:225], v[204:207], v[44:47]
	v_mfma_f32_16x16x32_bf16 v[40:43], v[232:235], v[204:207], v[40:43]
	v_mfma_f32_16x16x32_bf16 v[36:39], v[222:225], v[214:217], v[36:39]
	v_mfma_f32_16x16x32_bf16 v[32:35], v[232:235], v[214:217], v[32:35]
	v_mfma_f32_16x16x32_bf16 v[60:63], v[228:231], v[192:195], v[60:63]
	v_mfma_f32_16x16x32_bf16 v[56:59], v[236:239], v[192:195], v[56:59]
	v_mfma_f32_16x16x32_bf16 v[52:55], v[228:231], v[200:203], v[52:55]
	v_mfma_f32_16x16x32_bf16 v[48:51], v[236:239], v[200:203], v[48:51]
	v_mfma_f32_16x16x32_bf16 v[44:47], v[228:231], v[208:211], v[44:47]
	v_mfma_f32_16x16x32_bf16 v[40:43], v[236:239], v[208:211], v[40:43]
	v_mfma_f32_16x16x32_bf16 v[36:39], v[228:231], v[218:221], v[36:39]
	v_mfma_f32_16x16x32_bf16 v[32:35], v[236:239], v[218:221], v[32:35]
	s_setprio 0
	s_mov_b32 m0, s86
	v_lshl_add_u64 v[242:243], s[80:81], 0, v[128:129]
	s_barrier
	ds_read_b128 v[188:191], v171 offset:16384
	ds_read_b128 v[192:195], v171 offset:17408
	ds_read_b128 v[196:199], v171 offset:18432
	ds_read_b128 v[200:203], v171 offset:19456
	ds_read_b128 v[204:207], v171 offset:20480
	ds_read_b128 v[208:211], v171 offset:21504
	ds_read_b128 v[214:217], v171 offset:22528
	ds_read_b128 v[218:221], v171 offset:23552
	global_load_lds_dwordx4 v[242:243], off
	v_lshl_add_u64 v[244:245], s[80:81], 0, v[130:131]
	s_mov_b32 m0, s87
	s_nop 0
	global_load_lds_dwordx4 v[244:245], off
	s_barrier
	s_waitcnt lgkmcnt(0)
	s_setprio 1
	s_waitcnt lgkmcnt(0)
	v_mfma_f32_16x16x32_bf16 v[92:95], v[156:159], v[188:191], v[92:95]
	v_mfma_f32_16x16x32_bf16 v[88:91], v[180:183], v[188:191], v[88:91]
	v_mfma_f32_16x16x32_bf16 v[84:87], v[156:159], v[196:199], v[84:87]
	v_mfma_f32_16x16x32_bf16 v[80:83], v[180:183], v[196:199], v[80:83]
	v_mfma_f32_16x16x32_bf16 v[76:79], v[156:159], v[204:207], v[76:79]
	v_mfma_f32_16x16x32_bf16 v[72:75], v[180:183], v[204:207], v[72:75]
	v_mfma_f32_16x16x32_bf16 v[68:71], v[156:159], v[214:217], v[68:71]
	v_mfma_f32_16x16x32_bf16 v[64:67], v[180:183], v[214:217], v[64:67]
	v_mfma_f32_16x16x32_bf16 v[92:95], v[176:179], v[192:195], v[92:95]
	v_mfma_f32_16x16x32_bf16 v[88:91], v[184:187], v[192:195], v[88:91]
	v_mfma_f32_16x16x32_bf16 v[84:87], v[176:179], v[200:203], v[84:87]
	v_mfma_f32_16x16x32_bf16 v[80:83], v[184:187], v[200:203], v[80:83]
	v_mfma_f32_16x16x32_bf16 v[76:79], v[176:179], v[208:211], v[76:79]
	v_mfma_f32_16x16x32_bf16 v[72:75], v[184:187], v[208:211], v[72:75]
	v_mfma_f32_16x16x32_bf16 v[68:71], v[176:179], v[218:221], v[68:71]
	v_mfma_f32_16x16x32_bf16 v[64:67], v[184:187], v[218:221], v[64:67]
	s_setprio 0
	s_barrier
	s_add_u32 vcc_lo, s78, 0x80000
	s_addc_u32 vcc_hi, s79, 0
	s_add_i32 s33, s97, s85
	s_mov_b32 m0, s33
	s_nop 0
	global_load_lds_dwordx4 v132, vcc
	s_add_i32 m0, s33, 0x2000
	s_nop 0
	global_load_lds_dwordx4 v154, vcc
	s_cmp_lg_u32 s29, -2
	s_cbranch_scc1 .Lgh_p1_strict
	s_cmp_eq_u32 s99, 0
	s_cbranch_scc1 .Lgh_p1_strict
	s_waitcnt vmcnt(24)
	s_branch .Lgh_p1_join
.Lgh_p1_strict:
	s_waitcnt vmcnt(6)
.Lgh_p1_join:
	s_barrier
	s_setprio 1
	v_mfma_f32_16x16x32_bf16 v[28:31], v[222:225], v[188:191], v[28:31]
	v_mfma_f32_16x16x32_bf16 v[24:27], v[232:235], v[188:191], v[24:27]
	v_mfma_f32_16x16x32_bf16 v[20:23], v[222:225], v[196:199], v[20:23]
	v_mfma_f32_16x16x32_bf16 v[16:19], v[232:235], v[196:199], v[16:19]
	v_mfma_f32_16x16x32_bf16 v[12:15], v[222:225], v[204:207], v[12:15]
	v_mfma_f32_16x16x32_bf16 v[8:11], v[232:235], v[204:207], v[8:11]
	v_mfma_f32_16x16x32_bf16 v[4:7], v[222:225], v[214:217], v[4:7]
	v_mfma_f32_16x16x32_bf16 v[0:3], v[232:235], v[214:217], v[0:3]
	v_mfma_f32_16x16x32_bf16 v[28:31], v[228:231], v[192:195], v[28:31]
	v_mfma_f32_16x16x32_bf16 v[24:27], v[236:239], v[192:195], v[24:27]
	v_mfma_f32_16x16x32_bf16 v[20:23], v[228:231], v[200:203], v[20:23]
	v_mfma_f32_16x16x32_bf16 v[16:19], v[236:239], v[200:203], v[16:19]
	v_mfma_f32_16x16x32_bf16 v[12:15], v[228:231], v[208:211], v[12:15]
	v_mfma_f32_16x16x32_bf16 v[8:11], v[236:239], v[208:211], v[8:11]
	v_mfma_f32_16x16x32_bf16 v[4:7], v[228:231], v[218:221], v[4:7]
	v_mfma_f32_16x16x32_bf16 v[0:3], v[236:239], v[218:221], v[0:3]
	s_setprio 0
	s_add_i32 s33, 0, 0x18000
	v_add_u32_e32 v155, s33, v168
	s_barrier
	ds_read_b128 v[156:159], v155
	ds_read_b128 v[176:179], v155 offset:1024
	ds_read_b128 v[180:183], v155 offset:2048
	ds_read_b128 v[184:187], v155 offset:3072
	s_add_u32 s80, s80, 0x80000
	s_addc_u32 s81, s81, 0
	s_mov_b32 m0, s88
	v_lshl_add_u64 v[222:223], s[80:81], 0, v[128:129]
	ds_read_b128 v[188:191], v171 offset:32768
	ds_read_b128 v[192:195], v171 offset:33792
	ds_read_b128 v[196:199], v171 offset:34816
	ds_read_b128 v[200:203], v171 offset:35840
	ds_read_b128 v[204:207], v171 offset:36864
	ds_read_b128 v[208:211], v171 offset:37888
	ds_read_b128 v[214:217], v171 offset:38912
	ds_read_b128 v[218:221], v171 offset:39936
	global_load_lds_dwordx4 v[222:223], off
	v_lshl_add_u64 v[222:223], s[80:81], 0, v[130:131]
	s_mov_b32 m0, s89
	s_nop 0
	global_load_lds_dwordx4 v[222:223], off
	s_waitcnt lgkmcnt(8)
	s_barrier
	s_waitcnt lgkmcnt(0)
	s_setprio 1
	s_waitcnt lgkmcnt(0)
	v_mfma_f32_16x16x32_bf16 v[124:127], v[156:159], v[188:191], v[124:127]
	v_mfma_f32_16x16x32_bf16 v[120:123], v[180:183], v[188:191], v[120:123]
	v_mfma_f32_16x16x32_bf16 v[116:119], v[156:159], v[196:199], v[116:119]
	v_mfma_f32_16x16x32_bf16 v[112:115], v[180:183], v[196:199], v[112:115]
	v_mfma_f32_16x16x32_bf16 v[108:111], v[156:159], v[204:207], v[108:111]
	v_mfma_f32_16x16x32_bf16 v[104:107], v[180:183], v[204:207], v[104:107]
	v_mfma_f32_16x16x32_bf16 v[100:103], v[156:159], v[214:217], v[100:103]
	v_mfma_f32_16x16x32_bf16 v[96:99], v[180:183], v[214:217], v[96:99]
	v_mfma_f32_16x16x32_bf16 v[124:127], v[176:179], v[192:195], v[124:127]
	v_mfma_f32_16x16x32_bf16 v[120:123], v[184:187], v[192:195], v[120:123]
	v_mfma_f32_16x16x32_bf16 v[116:119], v[176:179], v[200:203], v[116:119]
	v_mfma_f32_16x16x32_bf16 v[112:115], v[184:187], v[200:203], v[112:115]
	v_mfma_f32_16x16x32_bf16 v[108:111], v[176:179], v[208:211], v[108:111]
	v_mfma_f32_16x16x32_bf16 v[104:107], v[184:187], v[208:211], v[104:107]
	v_mfma_f32_16x16x32_bf16 v[100:103], v[176:179], v[218:221], v[100:103]
	v_mfma_f32_16x16x32_bf16 v[96:99], v[184:187], v[218:221], v[96:99]
	s_setprio 0
	s_barrier
	s_add_i32 s80, 0, 0x1c000
	s_add_i32 s33, s33, s85
	v_add_u32_e32 v155, s80, v168
	v_lshl_add_u64 v[160:161], v[160:161], 0, s[14:15]
	s_mov_b32 m0, s33
	ds_read_b128 v[222:225], v155
	ds_read_b128 v[228:231], v155 offset:1024
	ds_read_b128 v[232:235], v155 offset:2048
	ds_read_b128 v[236:239], v155 offset:3072
	global_load_lds_dwordx4 v[160:161], off
	v_lshl_add_u64 v[160:161], v[240:241], 0, s[14:15]
	s_add_i32 m0, s33, 0x2000
	s_nop 0
	global_load_lds_dwordx4 v[160:161], off
	s_barrier
	s_waitcnt lgkmcnt(0)
	s_setprio 1
	s_waitcnt lgkmcnt(0)
	v_mfma_f32_16x16x32_bf16 v[60:63], v[222:225], v[188:191], v[60:63]
	v_mfma_f32_16x16x32_bf16 v[56:59], v[232:235], v[188:191], v[56:59]
	v_mfma_f32_16x16x32_bf16 v[52:55], v[222:225], v[196:199], v[52:55]
	v_mfma_f32_16x16x32_bf16 v[48:51], v[232:235], v[196:199], v[48:51]
	v_mfma_f32_16x16x32_bf16 v[44:47], v[222:225], v[204:207], v[44:47]
	v_mfma_f32_16x16x32_bf16 v[40:43], v[232:235], v[204:207], v[40:43]
	v_mfma_f32_16x16x32_bf16 v[36:39], v[222:225], v[214:217], v[36:39]
	v_mfma_f32_16x16x32_bf16 v[32:35], v[232:235], v[214:217], v[32:35]
	v_mfma_f32_16x16x32_bf16 v[60:63], v[228:231], v[192:195], v[60:63]
	v_mfma_f32_16x16x32_bf16 v[56:59], v[236:239], v[192:195], v[56:59]
	v_mfma_f32_16x16x32_bf16 v[52:55], v[228:231], v[200:203], v[52:55]
	v_mfma_f32_16x16x32_bf16 v[48:51], v[236:239], v[200:203], v[48:51]
	v_mfma_f32_16x16x32_bf16 v[44:47], v[228:231], v[208:211], v[44:47]
	v_mfma_f32_16x16x32_bf16 v[40:43], v[236:239], v[208:211], v[40:43]
	v_mfma_f32_16x16x32_bf16 v[36:39], v[228:231], v[218:221], v[36:39]
	v_mfma_f32_16x16x32_bf16 v[32:35], v[236:239], v[218:221], v[32:35]
	s_setprio 0
	s_mov_b32 m0, s91
	v_lshl_add_u64 v[160:161], v[242:243], 0, s[14:15]
	s_barrier
	ds_read_b128 v[188:191], v171 offset:49152
	ds_read_b128 v[192:195], v171 offset:50176
	ds_read_b128 v[196:199], v171 offset:51200
	ds_read_b128 v[200:203], v171 offset:52224
	ds_read_b128 v[204:207], v171 offset:53248
	ds_read_b128 v[208:211], v171 offset:54272
	ds_read_b128 v[214:217], v171 offset:55296
	ds_read_b128 v[218:221], v171 offset:56320
	global_load_lds_dwordx4 v[160:161], off
	v_lshl_add_u64 v[160:161], v[244:245], 0, s[14:15]
	s_mov_b32 m0, s92
	s_nop 0
	global_load_lds_dwordx4 v[160:161], off
	s_barrier
	s_waitcnt lgkmcnt(0)
	s_setprio 1
	s_waitcnt lgkmcnt(0)
	v_mfma_f32_16x16x32_bf16 v[92:95], v[156:159], v[188:191], v[92:95]
	v_mfma_f32_16x16x32_bf16 v[88:91], v[180:183], v[188:191], v[88:91]
	v_mfma_f32_16x16x32_bf16 v[84:87], v[156:159], v[196:199], v[84:87]
	v_mfma_f32_16x16x32_bf16 v[80:83], v[180:183], v[196:199], v[80:83]
	v_mfma_f32_16x16x32_bf16 v[76:79], v[156:159], v[204:207], v[76:79]
	v_mfma_f32_16x16x32_bf16 v[72:75], v[180:183], v[204:207], v[72:75]
	v_mfma_f32_16x16x32_bf16 v[68:71], v[156:159], v[214:217], v[68:71]
	v_mfma_f32_16x16x32_bf16 v[64:67], v[180:183], v[214:217], v[64:67]
	v_mfma_f32_16x16x32_bf16 v[92:95], v[176:179], v[192:195], v[92:95]
	v_mfma_f32_16x16x32_bf16 v[88:91], v[184:187], v[192:195], v[88:91]
	v_mfma_f32_16x16x32_bf16 v[84:87], v[176:179], v[200:203], v[84:87]
	v_mfma_f32_16x16x32_bf16 v[80:83], v[184:187], v[200:203], v[80:83]
	v_mfma_f32_16x16x32_bf16 v[76:79], v[176:179], v[208:211], v[76:79]
	v_mfma_f32_16x16x32_bf16 v[72:75], v[184:187], v[208:211], v[72:75]
	v_mfma_f32_16x16x32_bf16 v[68:71], v[176:179], v[218:221], v[68:71]
	v_mfma_f32_16x16x32_bf16 v[64:67], v[184:187], v[218:221], v[64:67]
	s_setprio 0
	s_barrier
	s_add_u32 s78, s78, 0x80080
	s_addc_u32 s79, s79, 0
	s_add_i32 s33, s80, s85
	s_mov_b32 m0, s33
	s_nop 0
	global_load_lds_dwordx4 v132, s[78:79]
	s_add_i32 m0, s33, 0x2000
	s_nop 0
	global_load_lds_dwordx4 v154, s[78:79]
	s_waitcnt vmcnt(6)
	s_barrier
	s_setprio 1
	v_mfma_f32_16x16x32_bf16 v[28:31], v[222:225], v[188:191], v[28:31]
	v_mfma_f32_16x16x32_bf16 v[24:27], v[232:235], v[188:191], v[24:27]
	v_mfma_f32_16x16x32_bf16 v[20:23], v[222:225], v[196:199], v[20:23]
	v_mfma_f32_16x16x32_bf16 v[16:19], v[232:235], v[196:199], v[16:19]
	v_mfma_f32_16x16x32_bf16 v[12:15], v[222:225], v[204:207], v[12:15]
	v_mfma_f32_16x16x32_bf16 v[8:11], v[232:235], v[204:207], v[8:11]
	v_mfma_f32_16x16x32_bf16 v[4:7], v[222:225], v[214:217], v[4:7]
	v_mfma_f32_16x16x32_bf16 v[0:3], v[232:235], v[214:217], v[0:3]
	v_mfma_f32_16x16x32_bf16 v[28:31], v[228:231], v[192:195], v[28:31]
	v_mfma_f32_16x16x32_bf16 v[24:27], v[236:239], v[192:195], v[24:27]
	v_mfma_f32_16x16x32_bf16 v[20:23], v[228:231], v[200:203], v[20:23]
	v_mfma_f32_16x16x32_bf16 v[16:19], v[236:239], v[200:203], v[16:19]
	v_mfma_f32_16x16x32_bf16 v[12:15], v[228:231], v[208:211], v[12:15]
	v_mfma_f32_16x16x32_bf16 v[8:11], v[236:239], v[208:211], v[8:11]
	v_mfma_f32_16x16x32_bf16 v[4:7], v[228:231], v[218:221], v[4:7]
	v_mfma_f32_16x16x32_bf16 v[0:3], v[236:239], v[218:221], v[0:3]
	s_setprio 0
	s_add_i32 s29, s29, 2
	s_add_u32 s76, s76, 0x100
	s_addc_u32 s77, s77, 0
	s_add_u32 s83, s83, 0x100
	s_addc_u32 s28, s28, 0
	s_cmp_gt_u32 s29, 29
	s_barrier
	s_cbranch_scc0 .LBB0_237
	s_add_u32 s100, s59, 0x80080
	s_addc_u32 s101, s9, 0
	s_mov_b32 s99, 1
	v_lshl_add_u64 v[154:155], s[100:101], 0, v[136:137]
	s_add_i32 m0, s86, 0xc000
	s_nop 0
	global_load_lds_dwordx4 v[154:155], off
	v_lshl_add_u64 v[154:155], s[100:101], 0, v[138:139]
	s_add_i32 m0, s86, 0xe000
	s_nop 0
	global_load_lds_dwordx4 v[154:155], off
	s_lshl_b32 s28, s74, 8
	s_and_b32 s6, s27, 4
	s_bitcmp1_b32 s27, 2
	s_cselect_b64 s[76:77], -1, 0
	s_cmp_eq_u32 s6, 0
	v_or_b32_e32 v160, s28, v169
	s_cbranch_scc1 .LBB0_240
	v_mul_hi_i32 v132, v160, s82
	v_lshrrev_b32_e32 v152, 31, v132
	v_lshrrev_b32_e32 v132, 5, v132
	v_add_u32_e32 v132, v132, v152
	v_mul_lo_u32 v132, v132, s95
	v_sub_u32_e32 v132, v160, v132
	v_add_u32_e32 v152, 0xffffff80, v132
	v_lshrrev_b32_e32 v152, 1, v152
	v_cmp_lt_i32_e32 vcc, s22, v132
	s_and_b64 s[78:79], vcc, exec
	s_nop 0
	v_cndmask_b32_e32 v132, 0, v152, vcc
	v_mov_b64_e32 v[154:155], v[132:133]
	s_branch .LBB0_241

.LBB0_682:
	s_mov_b32 s99, 0
	s_cmp_lt_i32 s44, 6
	s_cselect_b64 s[8:9], -1, 0
	s_and_b64 s[8:9], s[8:9], s[6:7]
	s_andn2_b64 vcc, exec, s[8:9]
	s_cbranch_vccnz .LBB0_699
	s_cmpk_gt_i32 s2, 0x1ff
	v_readfirstlane_b32 s3, v213
	s_cbranch_scc1 .LBB0_699
	v_lshrrev_b32_e32 v2, 1, v213
	v_lshrrev_b32_e32 v3, 5, v213
	v_and_b32_e32 v2, 24, v2
	v_and_b32_e32 v3, 4, v3
	v_bfe_u32 v4, v213, 2, 2
	v_lshlrev_b32_e32 v0, 4, v213
	v_and_b32_e32 v1, 32, v213
	v_bfe_u32 v10, v213, 2, 4
	v_or3_b32 v2, v3, v4, v2
	v_lshrrev_b32_e32 v3, 3, v213
	s_movk_i32 s6, 0x70
	s_add_u32 s52, s42, 0x5004000
	v_bitop3_b32 v8, v0, v1, 48 bitop3:0x6c
	v_and_b32_e32 v9, 64, v213
	v_and_or_b32 v4, v3, s6, v10
	s_movk_i32 s6, 0x60
	v_add_u32_e32 v11, 0x2000, v0
	s_addc_u32 s53, s43, 0
	v_or_b32_e32 v1, v8, v9
	v_and_or_b32 v3, v3, s6, v2
	v_lshrrev_b32_e32 v0, 7, v11
	s_movk_i32 s6, 0xf0
	s_add_u32 s54, s42, 0x1704000
	v_lshl_or_b32 v130, v3, 12, v1
	v_and_or_b32 v3, v0, s6, v10
	s_movk_i32 s6, 0xe0
	s_addc_u32 s55, s43, 0
	s_ashr_i32 s57, s2, 31
	v_and_or_b32 v0, v0, s6, v2
	s_lshr_b32 s6, s57, 29
	s_add_i32 s6, s2, s6
	s_and_b32 s10, s6, -8
	s_lshr_b32 s14, s3, 6
	s_sub_i32 s10, s2, s10
	s_lshr_b32 s7, s3, 8
	s_lshl_b32 s56, s14, 10
	s_lshl_b32 s12, s10, 6
	s_ashr_i32 s6, s6, 3
	s_mul_i32 s11, s10, 0x41
	s_cmp_lt_i32 s10, 0
	s_cselect_b32 s10, s11, s12
	s_add_i32 s6, s10, s6
	s_ashr_i32 s10, s6, 31
	s_lshr_b32 s10, s10, 26
	s_add_i32 s10, s6, s10
	s_ashr_i32 s11, s10, 6
	s_andn2_b32 s10, s10, 63
	s_sub_i32 s10, s6, s10
	s_bfe_i32 s6, s10, 0x80000
	s_bfe_u32 s6, s6, 0x3000c
	s_add_i32 s12, s10, s6
	s_bfe_i32 s6, s12, 0x80000
	s_and_b32 s12, s12, 0xf8
	s_sub_i32 s10, s10, s12
	s_lshl_b32 s11, s11, 3
	s_sext_i32_i8 s10, s10
	s_add_i32 s22, s11, s10
	s_sext_i32_i16 s6, s6
	s_ashr_i32 s23, s22, 31
	s_lshr_b32 s6, s6, 3
	s_lshl_b64 s[10:11], s[22:23], 20
	s_add_u32 s34, s52, s10
	s_addc_u32 s35, s53, s11
	s_bfe_i64 s[10:11], s[6:7], 0x100000
	s_lshl_b64 s[10:11], s[10:11], 20
	s_add_u32 s36, s54, s10
	s_addc_u32 s37, s55, s11
	s_add_i32 s23, s56, 0
	s_add_i32 m0, s23, 0x10000
	v_lshl_or_b32 v134, v0, 12, v1
	global_load_lds_dwordx4 v130, s[36:37]
	s_add_i32 m0, s23, 0x12000
	v_lshl_or_b32 v128, v4, 12, v1
	global_load_lds_dwordx4 v134, s[36:37]
	s_mov_b32 m0, s23
	s_add_i32 s58, s23, 0x2000
	v_lshl_or_b32 v132, v3, 12, v1
	global_load_lds_dwordx4 v128, s[34:35]
	s_mov_b32 m0, s58
	s_add_u32 s10, s36, 0x80000
	global_load_lds_dwordx4 v132, s[34:35]
	s_addc_u32 s11, s37, 0
	s_add_i32 m0, s23, 0x14000
	v_mov_b32_e32 v131, 0
	global_load_lds_dwordx4 v130, s[10:11]
	s_add_i32 m0, s23, 0x16000
	v_mov_b32_e32 v135, v131
	global_load_lds_dwordx4 v134, s[10:11]
	s_add_u32 s10, s34, 0x80000
	s_addc_u32 s11, s35, 0
	s_add_i32 s59, s23, 0x4000
	s_mov_b32 m0, s59
	s_add_i32 s60, s23, 0x6000
	global_load_lds_dwordx4 v128, s[10:11]
	s_mov_b32 m0, s60
	v_mov_b32_e32 v129, v131
	global_load_lds_dwordx4 v132, s[10:11]
	v_mov_b32_e32 v133, v131
	s_mov_b32 s61, 0
	v_lshl_add_u64 v[6:7], s[36:37], 0, v[130:131]
	v_lshl_add_u64 v[4:5], s[36:37], 0, v[134:135]
	v_lshl_add_u64 v[2:3], s[34:35], 0, v[128:129]
	v_lshl_add_u64 v[0:1], s[34:35], 0, v[132:133]
	s_cmp_lg_u32 s7, 1
	s_mov_b64 s[10:11], 0x80000
	s_cbranch_scc1 .LBB0_686
	s_barrier

.LBB0_694:
	ds_read_b128 v[150:153], v147
	ds_read_b128 v[154:157], v147 offset:1024
	ds_read_b128 v[158:161], v147 offset:2048
	ds_read_b128 v[162:165], v147 offset:3072
	s_add_u32 s33, s34, 0xfff80080
	s_addc_u32 s36, s35, -1
	s_cmp_eq_u32 s77, 28
	s_cselect_b32 s39, s27, s36
	s_cselect_b32 s38, s73, s33
	s_cselect_b32 s37, s25, s76
	s_cselect_b32 s36, s74, s75
	v_lshl_add_u64 v[198:199], s[34:35], 0, v[136:137]
	s_add_i32 m0, s23, 0xc000
	ds_read_b128 v[166:169], v148
	ds_read_b128 v[170:173], v148 offset:1024
	ds_read_b128 v[174:177], v148 offset:2048
	ds_read_b128 v[178:181], v148 offset:3072
	ds_read_b128 v[182:185], v148 offset:4096
	ds_read_b128 v[186:189], v148 offset:5120
	ds_read_b128 v[190:193], v148 offset:6144
	ds_read_b128 v[194:197], v148 offset:7168
	global_load_lds_dwordx4 v[198:199], off
	v_lshl_add_u64 v[198:199], s[34:35], 0, v[138:139]
	s_add_i32 m0, s23, 0xe000
	s_nop 0
	global_load_lds_dwordx4 v[198:199], off
	s_waitcnt lgkmcnt(8)
	s_barrier
	s_waitcnt lgkmcnt(0)
	s_setprio 1
	s_waitcnt lgkmcnt(0)
	v_mfma_f32_16x16x32_bf16 v[124:127], v[150:153], v[166:169], v[124:127]
	v_mfma_f32_16x16x32_bf16 v[120:123], v[158:161], v[166:169], v[120:123]
	v_mfma_f32_16x16x32_bf16 v[116:119], v[150:153], v[174:177], v[116:119]
	v_mfma_f32_16x16x32_bf16 v[112:115], v[158:161], v[174:177], v[112:115]
	v_mfma_f32_16x16x32_bf16 v[108:111], v[150:153], v[182:185], v[108:111]
	v_mfma_f32_16x16x32_bf16 v[104:107], v[158:161], v[182:185], v[104:107]
	v_mfma_f32_16x16x32_bf16 v[100:103], v[150:153], v[190:193], v[100:103]
	v_mfma_f32_16x16x32_bf16 v[96:99], v[158:161], v[190:193], v[96:99]
	v_mfma_f32_16x16x32_bf16 v[124:127], v[154:157], v[170:173], v[124:127]
	v_mfma_f32_16x16x32_bf16 v[120:123], v[162:165], v[170:173], v[120:123]
	v_mfma_f32_16x16x32_bf16 v[116:119], v[154:157], v[178:181], v[116:119]
	v_mfma_f32_16x16x32_bf16 v[112:115], v[162:165], v[178:181], v[112:115]
	v_mfma_f32_16x16x32_bf16 v[108:111], v[154:157], v[186:189], v[108:111]
	v_mfma_f32_16x16x32_bf16 v[104:107], v[162:165], v[186:189], v[104:107]
	v_mfma_f32_16x16x32_bf16 v[100:103], v[154:157], v[194:197], v[100:103]
	v_mfma_f32_16x16x32_bf16 v[96:99], v[162:165], v[194:197], v[96:99]
	s_setprio 0
	s_barrier
	s_add_i32 s33, s66, s56
	v_lshl_add_u64 v[210:211], s[36:37], 0, v[130:131]
	s_mov_b32 m0, s33
	ds_read_b128 v[198:201], v149
	ds_read_b128 v[202:205], v149 offset:1024
	ds_read_b128 v[206:209], v149 offset:2048
	ds_read_b128 v[216:219], v149 offset:3072
	global_load_lds_dwordx4 v[210:211], off
	v_lshl_add_u64 v[220:221], s[36:37], 0, v[134:135]
	s_add_i32 m0, s33, 0x2000
	s_nop 0
	global_load_lds_dwordx4 v[220:221], off
	s_barrier
	s_waitcnt lgkmcnt(0)
	s_setprio 1
	s_waitcnt lgkmcnt(0)
	v_mfma_f32_16x16x32_bf16 v[80:83], v[198:201], v[166:169], v[80:83]
	v_mfma_f32_16x16x32_bf16 v[72:75], v[206:209], v[166:169], v[72:75]
	v_mfma_f32_16x16x32_bf16 v[68:71], v[198:201], v[174:177], v[68:71]
	v_mfma_f32_16x16x32_bf16 v[60:63], v[206:209], v[174:177], v[60:63]
	v_mfma_f32_16x16x32_bf16 v[52:55], v[198:201], v[182:185], v[52:55]
	v_mfma_f32_16x16x32_bf16 v[48:51], v[206:209], v[182:185], v[48:51]
	v_mfma_f32_16x16x32_bf16 v[36:39], v[198:201], v[190:193], v[36:39]
	v_mfma_f32_16x16x32_bf16 v[32:35], v[206:209], v[190:193], v[32:35]
	v_mfma_f32_16x16x32_bf16 v[80:83], v[202:205], v[170:173], v[80:83]
	v_mfma_f32_16x16x32_bf16 v[72:75], v[216:219], v[170:173], v[72:75]
	v_mfma_f32_16x16x32_bf16 v[68:71], v[202:205], v[178:181], v[68:71]
	v_mfma_f32_16x16x32_bf16 v[60:63], v[216:219], v[178:181], v[60:63]
	v_mfma_f32_16x16x32_bf16 v[52:55], v[202:205], v[186:189], v[52:55]
	v_mfma_f32_16x16x32_bf16 v[48:51], v[216:219], v[186:189], v[48:51]
	v_mfma_f32_16x16x32_bf16 v[36:39], v[202:205], v[194:197], v[36:39]
	v_mfma_f32_16x16x32_bf16 v[32:35], v[216:219], v[194:197], v[32:35]
	s_setprio 0
	s_mov_b32 m0, s23
	v_lshl_add_u64 v[222:223], s[38:39], 0, v[128:129]
	s_barrier
	ds_read_b128 v[166:169], v148 offset:16384
	ds_read_b128 v[170:173], v148 offset:17408
	ds_read_b128 v[174:177], v148 offset:18432
	ds_read_b128 v[178:181], v148 offset:19456
	ds_read_b128 v[182:185], v148 offset:20480
	ds_read_b128 v[186:189], v148 offset:21504
	ds_read_b128 v[190:193], v148 offset:22528
	ds_read_b128 v[194:197], v148 offset:23552
	global_load_lds_dwordx4 v[222:223], off
	v_lshl_add_u64 v[224:225], s[38:39], 0, v[132:133]
	s_mov_b32 m0, s58
	s_nop 0
	global_load_lds_dwordx4 v[224:225], off
	s_barrier
	s_waitcnt lgkmcnt(0)
	s_setprio 1
	s_waitcnt lgkmcnt(0)
	v_mfma_f32_16x16x32_bf16 v[92:95], v[150:153], v[166:169], v[92:95]
	v_mfma_f32_16x16x32_bf16 v[88:91], v[158:161], v[166:169], v[88:91]
	v_mfma_f32_16x16x32_bf16 v[84:87], v[150:153], v[174:177], v[84:87]
	v_mfma_f32_16x16x32_bf16 v[76:79], v[158:161], v[174:177], v[76:79]
	v_mfma_f32_16x16x32_bf16 v[64:67], v[150:153], v[182:185], v[64:67]
	v_mfma_f32_16x16x32_bf16 v[56:59], v[158:161], v[182:185], v[56:59]
	v_mfma_f32_16x16x32_bf16 v[44:47], v[150:153], v[190:193], v[44:47]
	v_mfma_f32_16x16x32_bf16 v[40:43], v[158:161], v[190:193], v[40:43]
	v_mfma_f32_16x16x32_bf16 v[92:95], v[154:157], v[170:173], v[92:95]
	v_mfma_f32_16x16x32_bf16 v[88:91], v[162:165], v[170:173], v[88:91]
	v_mfma_f32_16x16x32_bf16 v[84:87], v[154:157], v[178:181], v[84:87]
	v_mfma_f32_16x16x32_bf16 v[76:79], v[162:165], v[178:181], v[76:79]
	v_mfma_f32_16x16x32_bf16 v[64:67], v[154:157], v[186:189], v[64:67]
	v_mfma_f32_16x16x32_bf16 v[56:59], v[162:165], v[186:189], v[56:59]
	v_mfma_f32_16x16x32_bf16 v[44:47], v[154:157], v[194:197], v[44:47]
	v_mfma_f32_16x16x32_bf16 v[40:43], v[162:165], v[194:197], v[40:43]
	s_setprio 0
	s_barrier
	s_add_u32 s78, s36, 0x80000
	s_addc_u32 s79, s37, 0
	s_add_i32 s33, s67, s56
	v_lshl_add_u64 v[150:151], s[78:79], 0, v[130:131]
	s_mov_b32 m0, s33
	s_nop 0
	global_load_lds_dwordx4 v[150:151], off
	v_lshl_add_u64 v[150:151], s[78:79], 0, v[134:135]
	s_add_i32 m0, s33, 0x2000
	s_nop 0
	global_load_lds_dwordx4 v[150:151], off
	s_cmp_lg_u32 s77, -2
	s_cbranch_scc1 .Lgh_p5_strict
	s_cmp_eq_u32 s99, 0
	s_cbranch_scc1 .Lgh_p5_strict
	s_waitcnt vmcnt(24)
	s_branch .Lgh_p5_join

.Lgh_p5_join:
	s_barrier
	s_setprio 1
	v_mfma_f32_16x16x32_bf16 v[28:31], v[198:201], v[166:169], v[28:31]
	v_mfma_f32_16x16x32_bf16 v[24:27], v[206:209], v[166:169], v[24:27]
	v_mfma_f32_16x16x32_bf16 v[20:23], v[198:201], v[174:177], v[20:23]
	v_mfma_f32_16x16x32_bf16 v[16:19], v[206:209], v[174:177], v[16:19]
	v_mfma_f32_16x16x32_bf16 v[12:15], v[198:201], v[182:185], v[12:15]
	v_mfma_f32_16x16x32_bf16 v[8:11], v[206:209], v[182:185], v[8:11]
	v_mfma_f32_16x16x32_bf16 v[4:7], v[198:201], v[190:193], v[4:7]
	v_mfma_f32_16x16x32_bf16 v[0:3], v[206:209], v[190:193], v[0:3]
	v_mfma_f32_16x16x32_bf16 v[28:31], v[202:205], v[170:173], v[28:31]
	v_mfma_f32_16x16x32_bf16 v[24:27], v[216:219], v[170:173], v[24:27]
	v_mfma_f32_16x16x32_bf16 v[20:23], v[202:205], v[178:181], v[20:23]
	v_mfma_f32_16x16x32_bf16 v[16:19], v[216:219], v[178:181], v[16:19]
	v_mfma_f32_16x16x32_bf16 v[12:15], v[202:205], v[186:189], v[12:15]
	v_mfma_f32_16x16x32_bf16 v[8:11], v[216:219], v[186:189], v[8:11]
	v_mfma_f32_16x16x32_bf16 v[4:7], v[202:205], v[194:197], v[4:7]
	v_mfma_f32_16x16x32_bf16 v[0:3], v[216:219], v[194:197], v[0:3]
	s_setprio 0
	s_add_i32 s33, 0, 0x18000
	v_add_u32_e32 v162, s33, v145
	s_barrier
	ds_read_b128 v[150:153], v162
	ds_read_b128 v[154:157], v162 offset:1024
	ds_read_b128 v[158:161], v162 offset:2048
	ds_read_b128 v[162:165], v162 offset:3072
	s_add_u32 s38, s38, 0x80000
	s_addc_u32 s39, s39, 0
	s_mov_b32 m0, s59
	v_lshl_add_u64 v[198:199], s[38:39], 0, v[128:129]
	ds_read_b128 v[166:169], v148 offset:32768
	ds_read_b128 v[170:173], v148 offset:33792
	ds_read_b128 v[174:177], v148 offset:34816
	ds_read_b128 v[178:181], v148 offset:35840
	ds_read_b128 v[182:185], v148 offset:36864
	ds_read_b128 v[186:189], v148 offset:37888
	ds_read_b128 v[190:193], v148 offset:38912
	ds_read_b128 v[194:197], v148 offset:39936
	global_load_lds_dwordx4 v[198:199], off
	v_lshl_add_u64 v[198:199], s[38:39], 0, v[132:133]
	s_mov_b32 m0, s60
	s_nop 0
	global_load_lds_dwordx4 v[198:199], off
	s_waitcnt lgkmcnt(8)
	s_barrier
	s_waitcnt lgkmcnt(0)
	s_setprio 1
	s_waitcnt lgkmcnt(0)
	v_mfma_f32_16x16x32_bf16 v[124:127], v[150:153], v[166:169], v[124:127]
	v_mfma_f32_16x16x32_bf16 v[120:123], v[158:161], v[166:169], v[120:123]
	v_mfma_f32_16x16x32_bf16 v[116:119], v[150:153], v[174:177], v[116:119]
	v_mfma_f32_16x16x32_bf16 v[112:115], v[158:161], v[174:177], v[112:115]
	v_mfma_f32_16x16x32_bf16 v[108:111], v[150:153], v[182:185], v[108:111]
	v_mfma_f32_16x16x32_bf16 v[104:107], v[158:161], v[182:185], v[104:107]
	v_mfma_f32_16x16x32_bf16 v[100:103], v[150:153], v[190:193], v[100:103]
	v_mfma_f32_16x16x32_bf16 v[96:99], v[158:161], v[190:193], v[96:99]
	v_mfma_f32_16x16x32_bf16 v[124:127], v[154:157], v[170:173], v[124:127]
	v_mfma_f32_16x16x32_bf16 v[120:123], v[162:165], v[170:173], v[120:123]
	v_mfma_f32_16x16x32_bf16 v[116:119], v[154:157], v[178:181], v[116:119]
	v_mfma_f32_16x16x32_bf16 v[112:115], v[162:165], v[178:181], v[112:115]
	v_mfma_f32_16x16x32_bf16 v[108:111], v[154:157], v[186:189], v[108:111]
	v_mfma_f32_16x16x32_bf16 v[104:107], v[162:165], v[186:189], v[104:107]
	v_mfma_f32_16x16x32_bf16 v[100:103], v[154:157], v[194:197], v[100:103]
	v_mfma_f32_16x16x32_bf16 v[96:99], v[162:165], v[194:197], v[96:99]
	s_setprio 0
	s_barrier
	s_add_i32 s38, 0, 0x1c000
	s_add_i32 s33, s33, s56
	v_add_u32_e32 v216, s38, v145
	v_lshl_add_u64 v[210:211], v[210:211], 0, s[14:15]
	s_mov_b32 m0, s33
	ds_read_b128 v[198:201], v216
	ds_read_b128 v[202:205], v216 offset:1024
	ds_read_b128 v[206:209], v216 offset:2048
	ds_read_b128 v[216:219], v216 offset:3072
	global_load_lds_dwordx4 v[210:211], off
	v_lshl_add_u64 v[210:211], v[220:221], 0, s[14:15]
	s_add_i32 m0, s33, 0x2000
	s_nop 0
	global_load_lds_dwordx4 v[210:211], off
	s_barrier
	s_waitcnt lgkmcnt(0)
	s_setprio 1
	s_waitcnt lgkmcnt(0)
	v_mfma_f32_16x16x32_bf16 v[80:83], v[198:201], v[166:169], v[80:83]
	v_mfma_f32_16x16x32_bf16 v[72:75], v[206:209], v[166:169], v[72:75]
	v_mfma_f32_16x16x32_bf16 v[68:71], v[198:201], v[174:177], v[68:71]
	v_mfma_f32_16x16x32_bf16 v[60:63], v[206:209], v[174:177], v[60:63]
	v_mfma_f32_16x16x32_bf16 v[52:55], v[198:201], v[182:185], v[52:55]
	v_mfma_f32_16x16x32_bf16 v[48:51], v[206:209], v[182:185], v[48:51]
	v_mfma_f32_16x16x32_bf16 v[36:39], v[198:201], v[190:193], v[36:39]
	v_mfma_f32_16x16x32_bf16 v[32:35], v[206:209], v[190:193], v[32:35]
	v_mfma_f32_16x16x32_bf16 v[80:83], v[202:205], v[170:173], v[80:83]
	v_mfma_f32_16x16x32_bf16 v[72:75], v[216:219], v[170:173], v[72:75]
	v_mfma_f32_16x16x32_bf16 v[68:71], v[202:205], v[178:181], v[68:71]
	v_mfma_f32_16x16x32_bf16 v[60:63], v[216:219], v[178:181], v[60:63]
	v_mfma_f32_16x16x32_bf16 v[52:55], v[202:205], v[186:189], v[52:55]
	v_mfma_f32_16x16x32_bf16 v[48:51], v[216:219], v[186:189], v[48:51]
	v_mfma_f32_16x16x32_bf16 v[36:39], v[202:205], v[194:197], v[36:39]
	v_mfma_f32_16x16x32_bf16 v[32:35], v[216:219], v[194:197], v[32:35]
	s_setprio 0
	s_mov_b32 m0, s63
	v_lshl_add_u64 v[210:211], v[222:223], 0, s[14:15]
	s_barrier
	ds_read_b128 v[166:169], v148 offset:49152
	ds_read_b128 v[170:173], v148 offset:50176
	ds_read_b128 v[174:177], v148 offset:51200
	ds_read_b128 v[178:181], v148 offset:52224
	ds_read_b128 v[182:185], v148 offset:53248
	ds_read_b128 v[186:189], v148 offset:54272
	ds_read_b128 v[190:193], v148 offset:55296
	ds_read_b128 v[194:197], v148 offset:56320
	global_load_lds_dwordx4 v[210:211], off
	v_lshl_add_u64 v[210:211], v[224:225], 0, s[14:15]
	s_mov_b32 m0, s64
	s_nop 0
	global_load_lds_dwordx4 v[210:211], off
	s_barrier
	s_waitcnt lgkmcnt(0)
	s_setprio 1
	s_waitcnt lgkmcnt(0)
	v_mfma_f32_16x16x32_bf16 v[92:95], v[150:153], v[166:169], v[92:95]
	v_mfma_f32_16x16x32_bf16 v[88:91], v[158:161], v[166:169], v[88:91]
	v_mfma_f32_16x16x32_bf16 v[84:87], v[150:153], v[174:177], v[84:87]
	v_mfma_f32_16x16x32_bf16 v[76:79], v[158:161], v[174:177], v[76:79]
	v_mfma_f32_16x16x32_bf16 v[64:67], v[150:153], v[182:185], v[64:67]
	v_mfma_f32_16x16x32_bf16 v[56:59], v[158:161], v[182:185], v[56:59]
	v_mfma_f32_16x16x32_bf16 v[44:47], v[150:153], v[190:193], v[44:47]
	v_mfma_f32_16x16x32_bf16 v[40:43], v[158:161], v[190:193], v[40:43]
	v_mfma_f32_16x16x32_bf16 v[92:95], v[154:157], v[170:173], v[92:95]
	v_mfma_f32_16x16x32_bf16 v[88:91], v[162:165], v[170:173], v[88:91]
	v_mfma_f32_16x16x32_bf16 v[84:87], v[154:157], v[178:181], v[84:87]
	v_mfma_f32_16x16x32_bf16 v[76:79], v[162:165], v[178:181], v[76:79]
	v_mfma_f32_16x16x32_bf16 v[64:67], v[154:157], v[186:189], v[64:67]
	v_mfma_f32_16x16x32_bf16 v[56:59], v[162:165], v[186:189], v[56:59]
	v_mfma_f32_16x16x32_bf16 v[44:47], v[154:157], v[194:197], v[44:47]
	v_mfma_f32_16x16x32_bf16 v[40:43], v[162:165], v[194:197], v[40:43]
	s_setprio 0
	s_barrier
	s_add_u32 s36, s36, 0x80080
	s_addc_u32 s37, s37, 0
	s_add_i32 s33, s38, s56
	v_lshl_add_u64 v[150:151], s[36:37], 0, v[130:131]
	s_mov_b32 m0, s33
	s_nop 0
	global_load_lds_dwordx4 v[150:151], off
	v_lshl_add_u64 v[150:151], s[36:37], 0, v[134:135]
	s_add_i32 m0, s33, 0x2000
	s_nop 0
	global_load_lds_dwordx4 v[150:151], off
	s_waitcnt vmcnt(6)
	s_barrier
	s_setprio 1
	v_mfma_f32_16x16x32_bf16 v[28:31], v[198:201], v[166:169], v[28:31]
	v_mfma_f32_16x16x32_bf16 v[24:27], v[206:209], v[166:169], v[24:27]
	v_mfma_f32_16x16x32_bf16 v[20:23], v[198:201], v[174:177], v[20:23]
	v_mfma_f32_16x16x32_bf16 v[16:19], v[206:209], v[174:177], v[16:19]
	v_mfma_f32_16x16x32_bf16 v[12:15], v[198:201], v[182:185], v[12:15]
	v_mfma_f32_16x16x32_bf16 v[8:11], v[206:209], v[182:185], v[8:11]
	v_mfma_f32_16x16x32_bf16 v[4:7], v[198:201], v[190:193], v[4:7]
	v_mfma_f32_16x16x32_bf16 v[0:3], v[206:209], v[190:193], v[0:3]
	v_mfma_f32_16x16x32_bf16 v[28:31], v[202:205], v[170:173], v[28:31]
	v_mfma_f32_16x16x32_bf16 v[24:27], v[216:219], v[170:173], v[24:27]
	v_mfma_f32_16x16x32_bf16 v[20:23], v[202:205], v[178:181], v[20:23]
	v_mfma_f32_16x16x32_bf16 v[16:19], v[216:219], v[178:181], v[16:19]
	v_mfma_f32_16x16x32_bf16 v[12:15], v[202:205], v[186:189], v[12:15]
	v_mfma_f32_16x16x32_bf16 v[8:11], v[216:219], v[186:189], v[8:11]
	v_mfma_f32_16x16x32_bf16 v[4:7], v[202:205], v[194:197], v[4:7]
	v_mfma_f32_16x16x32_bf16 v[0:3], v[216:219], v[194:197], v[0:3]
	s_setprio 0
	s_add_i32 s77, s77, 2
	s_add_u32 s34, s34, 0x100
	s_addc_u32 s35, s35, 0
	s_add_u32 s75, s75, 0x100
	s_addc_u32 s76, s76, 0
	s_cmp_gt_u32 s77, 29
	s_barrier
	s_cbranch_scc0 .LBB0_694
	s_add_u32 s100, s73, 0x80080
	s_addc_u32 s101, s27, 0
	s_mov_b32 s99, 1
	v_lshl_add_u64 v[198:199], s[100:101], 0, v[136:137]
	s_add_i32 m0, s23, 0xc000
	s_nop 0
	global_load_lds_dwordx4 v[198:199], off
	v_lshl_add_u64 v[198:199], s[100:101], 0, v[138:139]
	s_add_i32 m0, s23, 0xe000
	s_nop 0
	global_load_lds_dwordx4 v[198:199], off
	v_lshl_add_u32 v150, s22, 8, v144
	v_lshl_or_b32 v152, s72, 8, v146
	v_ashrrev_i32_e32 v151, 31, v150
	v_ashrrev_i32_e32 v153, 31, v152
	v_cvt_pk_bf16_f32 v124, v124, v125
	v_cvt_pk_bf16_f32 v125, v126, v127
	v_cvt_pk_bf16_f32 v126, v120, v121
	v_lshlrev_b64 v[120:121], 12, v[150:151]
	v_cvt_pk_bf16_f32 v127, v122, v123
	v_lshl_add_u64 v[120:121], s[12:13], 0, v[120:121]
	v_lshlrev_b64 v[122:123], 1, v[152:153]
	v_lshl_add_u64 v[120:121], v[120:121], 0, v[122:123]
	v_cvt_pk_bf16_f32 v92, v92, v93
	v_cvt_pk_bf16_f32 v93, v94, v95
	v_cvt_pk_bf16_f32 v95, v90, v91
	v_add_co_u32_e32 v90, vcc, s68, v120
	v_cvt_pk_bf16_f32 v84, v84, v85
	s_nop 0
	v_addc_co_u32_e32 v91, vcc, 0, v121, vcc
	v_cvt_pk_bf16_f32 v85, v86, v87
	v_cvt_pk_bf16_f32 v87, v78, v79
	v_add_co_u32_e32 v78, vcc, s69, v120
	v_cvt_pk_bf16_f32 v64, v64, v65
	s_nop 0
	v_addc_co_u32_e32 v79, vcc, 0, v121, vcc
	v_cvt_pk_bf16_f32 v65, v66, v67
	v_cvt_pk_bf16_f32 v67, v58, v59
	v_add_co_u32_e32 v58, vcc, s70, v120
	global_store_dwordx4 v[120:121], v[124:127], off sc1
	s_nop 0
	v_addc_co_u32_e32 v59, vcc, 0, v121, vcc
	v_or_b32_e32 v124, 16, v150
	v_cvt_pk_bf16_f32 v116, v116, v117
	v_cvt_pk_bf16_f32 v117, v118, v119
	v_cvt_pk_bf16_f32 v119, v114, v115
	v_ashrrev_i32_e32 v125, 31, v124
	v_or_b32_e32 v114, 32, v150
	v_cvt_pk_bf16_f32 v108, v108, v109
	v_cvt_pk_bf16_f32 v109, v110, v111
	v_cvt_pk_bf16_f32 v111, v106, v107
	v_or_b32_e32 v106, 48, v150
	v_cvt_pk_bf16_f32 v44, v44, v45
	v_cvt_pk_bf16_f32 v45, v46, v47
	v_cvt_pk_bf16_f32 v46, v40, v41
	v_add_co_u32_e32 v40, vcc, s71, v120
	v_cvt_pk_bf16_f32 v118, v112, v113
	v_lshlrev_b64 v[112:113], 12, v[124:125]
	v_ashrrev_i32_e32 v115, 31, v114
	v_ashrrev_i32_e32 v107, 31, v106
	v_cvt_pk_bf16_f32 v47, v42, v43
	v_addc_co_u32_e32 v41, vcc, 0, v121, vcc
	v_lshl_add_u64 v[112:113], s[12:13], 0, v[112:113]
	v_cvt_pk_bf16_f32 v110, v104, v105
	v_lshlrev_b64 v[104:105], 12, v[114:115]
	v_cvt_pk_bf16_f32 v100, v100, v101
	v_cvt_pk_bf16_f32 v101, v102, v103
	v_cvt_pk_bf16_f32 v102, v96, v97
	v_lshlrev_b64 v[96:97], 12, v[106:107]
	global_store_dwordx4 v[40:41], v[44:47], off sc1
	v_cvt_pk_bf16_f32 v40, v80, v81
	v_cvt_pk_bf16_f32 v41, v82, v83
	v_cvt_pk_bf16_f32 v42, v72, v73
	v_cvt_pk_bf16_f32 v43, v74, v75
	v_lshl_add_u64 v[112:113], v[112:113], 0, v[122:123]
	v_lshl_add_u64 v[104:105], s[12:13], 0, v[104:105]
	v_lshl_add_u64 v[96:97], s[12:13], 0, v[96:97]
	v_cvt_pk_bf16_f32 v66, v56, v57
	global_store_dwordx4 v[120:121], v[40:43], off offset:256 sc1
	v_lshl_add_u64 v[104:105], v[104:105], 0, v[122:123]
	v_cvt_pk_bf16_f32 v103, v98, v99
	v_cvt_pk_bf16_f32 v40, v68, v69
	v_cvt_pk_bf16_f32 v41, v70, v71
	v_cvt_pk_bf16_f32 v42, v60, v61
	v_cvt_pk_bf16_f32 v43, v62, v63
	v_lshl_add_u64 v[96:97], v[96:97], 0, v[122:123]
	v_cvt_pk_bf16_f32 v94, v88, v89
	v_lshl_add_u64 v[88:89], v[120:121], 0, s[10:11]
	v_cvt_pk_bf16_f32 v86, v76, v77
	v_lshl_add_u64 v[76:77], v[120:121], 0, s[16:17]
	v_lshl_add_u64 v[56:57], v[120:121], 0, s[18:19]
	global_store_dwordx4 v[58:59], v[64:67], off sc1
	v_lshl_add_u64 v[58:59], v[120:121], 0, s[20:21]
	global_store_dwordx4 v[112:113], v[40:43], off offset:256 sc1
	v_cvt_pk_bf16_f32 v36, v36, v37
	v_cvt_pk_bf16_f32 v37, v38, v39
	v_cvt_pk_bf16_f32 v40, v52, v53
	v_cvt_pk_bf16_f32 v41, v54, v55
	v_cvt_pk_bf16_f32 v42, v48, v49
	v_cvt_pk_bf16_f32 v43, v50, v51
	v_cvt_pk_bf16_f32 v38, v32, v33
	v_cvt_pk_bf16_f32 v39, v34, v35
	v_cvt_pk_bf16_f32 v28, v28, v29
	v_cvt_pk_bf16_f32 v29, v30, v31
	v_cvt_pk_bf16_f32 v30, v24, v25
	v_cvt_pk_bf16_f32 v31, v26, v27
	v_cvt_pk_bf16_f32 v20, v20, v21
	v_cvt_pk_bf16_f32 v21, v22, v23
	v_cvt_pk_bf16_f32 v22, v16, v17
	v_cvt_pk_bf16_f32 v23, v18, v19
	v_cvt_pk_bf16_f32 v12, v12, v13
	v_cvt_pk_bf16_f32 v13, v14, v15
	v_cvt_pk_bf16_f32 v14, v8, v9
	v_cvt_pk_bf16_f32 v15, v10, v11
	v_cvt_pk_bf16_f32 v4, v4, v5
	v_cvt_pk_bf16_f32 v5, v6, v7
	v_cvt_pk_bf16_f32 v6, v0, v1
	v_cvt_pk_bf16_f32 v7, v2, v3
	s_and_b64 vcc, exec, s[6:7]
	s_mov_b32 s22, s26
	s_mov_b32 s72, s24
	s_mov_b64 s[36:37], s[30:31]
	s_mov_b64 s[34:35], s[28:29]
	global_store_dwordx4 v[112:113], v[116:119], off sc1
	global_store_dwordx4 v[104:105], v[108:111], off sc1
	global_store_dwordx4 v[96:97], v[100:103], off sc1
	global_store_dwordx4 v[90:91], v[92:95], off sc1
	global_store_dwordx4 v[78:79], v[84:87], off sc1
	global_store_dwordx4 v[104:105], v[40:43], off offset:256 sc1
	global_store_dwordx4 v[96:97], v[36:39], off offset:256 sc1
	global_store_dwordx4 v[88:89], v[28:31], off offset:256 sc1
	global_store_dwordx4 v[76:77], v[20:23], off offset:256 sc1
	global_store_dwordx4 v[56:57], v[12:15], off offset:256 sc1
	global_store_dwordx4 v[58:59], v[4:7], off offset:256 sc1
	s_cbranch_vccz .LBB0_687
	s_waitcnt vmcnt(0)
	s_cmpk_gt_u32 s3, 0xff
	s_cbranch_scc1 .LBB0_698
	s_barrier

.LBB0_812:
	s_mov_b32 s99, 0
	s_cmp_lt_i32 s44, 8
	s_cselect_b64 s[6:7], -1, 0
	s_and_b64 s[16:17], s[6:7], s[8:9]
	s_andn2_b64 vcc, exec, s[16:17]
	s_cbranch_vccnz .LBB0_911
	v_readfirstlane_b32 s3, v213
	s_cmpk_gt_i32 s2, 0x3bf
	v_lshlrev_b32_e32 v144, 2, v213
	s_cbranch_scc1 .LBB0_825
	v_lshrrev_b32_e32 v2, 1, v213
	v_and_b32_e32 v0, 4, v198
	v_bfe_u32 v1, v213, 2, 2
	v_and_b32_e32 v2, 24, v2
	v_or3_b32 v0, v0, v1, v2
	v_lshlrev_b32_e32 v1, 4, v213
	s_lshr_b32 s10, s3, 6
	v_add_u32_e32 v8, 0x2000, v1
	v_and_b32_e32 v4, 32, v213
	s_lshr_b32 s7, s3, 8
	s_lshl_b32 s30, s10, 10
	v_lshrrev_b32_e32 v2, 7, v8
	s_movk_i32 s6, 0xe0
	v_bitop3_b32 v9, v1, v4, 48 bitop3:0x6c
	v_and_b32_e32 v10, 64, v213
	v_and_or_b32 v3, v2, s6, v0
	v_or_b32_e32 v1, v9, v10
	s_add_u32 s31, s42, 0x2704000
	v_lshl_or_b32 v128, v3, 12, v1
	v_lshrrev_b32_e32 v3, 3, v213
	s_movk_i32 s6, 0x60
	s_addc_u32 s34, s43, 0
	v_and_or_b32 v0, v3, s6, v0
	v_bfe_u32 v11, v213, 2, 4
	s_movk_i32 s6, 0xf0
	s_add_u32 s35, s42, 0x5004000
	v_lshl_or_b32 v130, v0, 12, v1
	v_and_or_b32 v0, v2, s6, v11
	s_movk_i32 s6, 0x70
	s_addc_u32 s36, s43, 0
	s_ashr_i32 s37, s2, 31
	v_lshl_or_b32 v132, v0, 12, v1
	v_and_or_b32 v0, v3, s6, v11
	s_lshr_b32 s6, s37, 29
	s_add_i32 s6, s2, s6
	s_ashr_i32 s8, s6, 3
	s_and_b32 s6, s6, -8
	s_sub_i32 s6, s2, s6
	s_cmp_lt_i32 s6, 0
	s_movk_i32 s38, 0x79
	s_cselect_b32 s9, s38, 0x78
	s_mul_i32 s6, s9, s6
	s_add_i32 s6, s6, s8
	s_mul_hi_i32 s8, s6, 0x88888889
	s_add_i32 s8, s8, s6
	s_lshr_b32 s9, s8, 31
	s_ashr_i32 s8, s8, 6
	s_add_i32 s8, s8, s9
	s_lshl_b32 s9, s8, 3
	s_mulk_i32 s8, 0x78
	s_sub_i32 s8, s6, s8
	s_bfe_i32 s6, s8, 0x80000
	s_bfe_u32 s6, s6, 0x3000c
	s_add_i32 s11, s8, s6
	s_bfe_i32 s6, s11, 0x80000
	s_and_b32 s11, s11, 0xf8
	s_sub_i32 s8, s8, s11
	s_sext_i32_i8 s8, s8
	s_add_i32 s12, s9, s8
	s_sext_i32_i16 s6, s6
	s_ashr_i32 s13, s12, 31
	s_lshr_b32 s6, s6, 3
	s_lshl_b64 s[8:9], s[12:13], 20
	s_add_u32 s24, s35, s8
	s_addc_u32 s25, s36, s9
	s_bfe_i64 s[8:9], s[6:7], 0x100000
	s_lshl_b64 s[8:9], s[8:9], 20
	s_add_u32 s26, s31, s8
	s_addc_u32 s27, s34, s9
	s_add_i32 s13, s30, 0
	s_add_i32 m0, s13, 0x10000
	v_lshl_or_b32 v134, v0, 12, v1
	global_load_lds_dwordx4 v130, s[26:27]
	s_add_i32 m0, s13, 0x12000
	s_add_i32 s39, s13, 0x2000
	global_load_lds_dwordx4 v128, s[26:27]
	s_mov_b32 m0, s13
	s_add_u32 s8, s26, 0x80000
	global_load_lds_dwordx4 v134, s[24:25]
	s_mov_b32 m0, s39
	s_addc_u32 s9, s27, 0
	global_load_lds_dwordx4 v132, s[24:25]
	s_add_i32 m0, s13, 0x14000
	v_mov_b32_e32 v131, 0
	global_load_lds_dwordx4 v130, s[8:9]
	s_add_i32 m0, s13, 0x16000
	v_mov_b32_e32 v129, v131
	global_load_lds_dwordx4 v128, s[8:9]
	s_add_u32 s8, s24, 0x80000
	s_addc_u32 s9, s25, 0
	s_add_i32 s52, s13, 0x4000
	s_mov_b32 m0, s52
	s_add_i32 s53, s13, 0x6000
	global_load_lds_dwordx4 v134, s[8:9]
	s_mov_b32 m0, s53
	v_mov_b32_e32 v135, v131
	global_load_lds_dwordx4 v132, s[8:9]
	v_mov_b32_e32 v133, v131
	s_mov_b32 s54, 0
	v_lshl_add_u64 v[6:7], s[26:27], 0, v[130:131]
	v_lshl_add_u64 v[4:5], s[26:27], 0, v[128:129]
	v_lshl_add_u64 v[2:3], s[24:25], 0, v[134:135]
	s_cmp_lg_u32 s7, 1
	v_lshl_add_u64 v[0:1], s[24:25], 0, v[132:133]
	s_cbranch_scc1 .LBB0_816
	s_barrier

.LBB0_820:
	ds_read_b128 v[152:155], v148
	ds_read_b128 v[156:159], v148 offset:1024
	ds_read_b128 v[160:163], v148 offset:2048
	ds_read_b128 v[164:167], v148 offset:3072
	s_add_u32 s26, s24, 0xfff80080
	s_addc_u32 s27, s25, -1
	s_cmp_eq_u32 s67, 28
	s_cselect_b32 s29, s19, s27
	s_cselect_b32 s28, s63, s26
	s_cselect_b32 s27, s15, s66
	s_cselect_b32 s26, s64, s65
	v_lshl_add_u64 v[196:197], s[24:25], 0, v[136:137]
	s_add_i32 m0, s13, 0xc000
	ds_read_b128 v[168:171], v149
	ds_read_b128 v[172:175], v149 offset:1024
	ds_read_b128 v[176:179], v149 offset:2048
	ds_read_b128 v[180:183], v149 offset:3072
	ds_read_b128 v[184:187], v149 offset:4096
	ds_read_b128 v[188:191], v149 offset:5120
	ds_read_b128 v[192:195], v149 offset:6144
	ds_read_b128 v[200:203], v149 offset:7168
	global_load_lds_dwordx4 v[196:197], off
	v_lshl_add_u64 v[196:197], s[24:25], 0, v[138:139]
	s_add_i32 m0, s13, 0xe000
	s_nop 0
	global_load_lds_dwordx4 v[196:197], off
	s_waitcnt lgkmcnt(8)
	s_barrier
	s_waitcnt lgkmcnt(0)
	s_setprio 1
	s_waitcnt lgkmcnt(0)
	v_mfma_f32_16x16x32_bf16 v[124:127], v[152:155], v[168:171], v[124:127]
	v_mfma_f32_16x16x32_bf16 v[120:123], v[160:163], v[168:171], v[120:123]
	v_mfma_f32_16x16x32_bf16 v[116:119], v[152:155], v[176:179], v[116:119]
	v_mfma_f32_16x16x32_bf16 v[112:115], v[160:163], v[176:179], v[112:115]
	v_mfma_f32_16x16x32_bf16 v[108:111], v[152:155], v[184:187], v[108:111]
	v_mfma_f32_16x16x32_bf16 v[104:107], v[160:163], v[184:187], v[104:107]
	v_mfma_f32_16x16x32_bf16 v[100:103], v[152:155], v[192:195], v[100:103]
	v_mfma_f32_16x16x32_bf16 v[96:99], v[160:163], v[192:195], v[96:99]
	v_mfma_f32_16x16x32_bf16 v[124:127], v[156:159], v[172:175], v[124:127]
	v_mfma_f32_16x16x32_bf16 v[120:123], v[164:167], v[172:175], v[120:123]
	v_mfma_f32_16x16x32_bf16 v[116:119], v[156:159], v[180:183], v[116:119]
	v_mfma_f32_16x16x32_bf16 v[112:115], v[164:167], v[180:183], v[112:115]
	v_mfma_f32_16x16x32_bf16 v[108:111], v[156:159], v[188:191], v[108:111]
	v_mfma_f32_16x16x32_bf16 v[104:107], v[164:167], v[188:191], v[104:107]
	v_mfma_f32_16x16x32_bf16 v[100:103], v[156:159], v[200:203], v[100:103]
	v_mfma_f32_16x16x32_bf16 v[96:99], v[164:167], v[200:203], v[96:99]
	s_setprio 0
	s_barrier
	s_add_i32 s33, s59, s30
	v_lshl_add_u64 v[196:197], s[26:27], 0, v[130:131]
	s_mov_b32 m0, s33
	ds_read_b128 v[204:207], v150
	ds_read_b128 v[208:211], v150 offset:1024
	ds_read_b128 v[216:219], v150 offset:2048
	ds_read_b128 v[220:223], v150 offset:3072
	global_load_lds_dwordx4 v[196:197], off
	v_lshl_add_u64 v[224:225], s[26:27], 0, v[128:129]
	s_add_i32 m0, s33, 0x2000
	s_nop 0
	global_load_lds_dwordx4 v[224:225], off
	s_barrier
	s_waitcnt lgkmcnt(0)
	s_setprio 1
	s_waitcnt lgkmcnt(0)
	v_mfma_f32_16x16x32_bf16 v[84:87], v[204:207], v[168:171], v[84:87]
	v_mfma_f32_16x16x32_bf16 v[76:79], v[216:219], v[168:171], v[76:79]
	v_mfma_f32_16x16x32_bf16 v[68:71], v[204:207], v[176:179], v[68:71]
	v_mfma_f32_16x16x32_bf16 v[64:67], v[216:219], v[176:179], v[64:67]
	v_mfma_f32_16x16x32_bf16 v[52:55], v[204:207], v[184:187], v[52:55]
	v_mfma_f32_16x16x32_bf16 v[48:51], v[216:219], v[184:187], v[48:51]
	v_mfma_f32_16x16x32_bf16 v[40:43], v[204:207], v[192:195], v[40:43]
	v_mfma_f32_16x16x32_bf16 v[32:35], v[216:219], v[192:195], v[32:35]
	v_mfma_f32_16x16x32_bf16 v[84:87], v[208:211], v[172:175], v[84:87]
	v_mfma_f32_16x16x32_bf16 v[76:79], v[220:223], v[172:175], v[76:79]
	v_mfma_f32_16x16x32_bf16 v[68:71], v[208:211], v[180:183], v[68:71]
	v_mfma_f32_16x16x32_bf16 v[64:67], v[220:223], v[180:183], v[64:67]
	v_mfma_f32_16x16x32_bf16 v[52:55], v[208:211], v[188:191], v[52:55]
	v_mfma_f32_16x16x32_bf16 v[48:51], v[220:223], v[188:191], v[48:51]
	v_mfma_f32_16x16x32_bf16 v[40:43], v[208:211], v[200:203], v[40:43]
	v_mfma_f32_16x16x32_bf16 v[32:35], v[220:223], v[200:203], v[32:35]
	s_setprio 0
	s_mov_b32 m0, s13
	v_lshl_add_u64 v[230:231], s[28:29], 0, v[134:135]
	s_barrier
	ds_read_b128 v[168:171], v149 offset:16384
	ds_read_b128 v[172:175], v149 offset:17408
	ds_read_b128 v[176:179], v149 offset:18432
	ds_read_b128 v[180:183], v149 offset:19456
	ds_read_b128 v[184:187], v149 offset:20480
	ds_read_b128 v[188:191], v149 offset:21504
	ds_read_b128 v[192:195], v149 offset:22528
	ds_read_b128 v[200:203], v149 offset:23552
	global_load_lds_dwordx4 v[230:231], off
	v_lshl_add_u64 v[232:233], s[28:29], 0, v[132:133]
	s_mov_b32 m0, s39
	s_nop 0
	global_load_lds_dwordx4 v[232:233], off
	s_barrier
	s_waitcnt lgkmcnt(0)
	s_setprio 1
	s_waitcnt lgkmcnt(0)
	v_mfma_f32_16x16x32_bf16 v[92:95], v[152:155], v[168:171], v[92:95]
	v_mfma_f32_16x16x32_bf16 v[88:91], v[160:163], v[168:171], v[88:91]
	v_mfma_f32_16x16x32_bf16 v[80:83], v[152:155], v[176:179], v[80:83]
	v_mfma_f32_16x16x32_bf16 v[72:75], v[160:163], v[176:179], v[72:75]
	v_mfma_f32_16x16x32_bf16 v[60:63], v[152:155], v[184:187], v[60:63]
	v_mfma_f32_16x16x32_bf16 v[56:59], v[160:163], v[184:187], v[56:59]
	v_mfma_f32_16x16x32_bf16 v[44:47], v[152:155], v[192:195], v[44:47]
	v_mfma_f32_16x16x32_bf16 v[36:39], v[160:163], v[192:195], v[36:39]
	v_mfma_f32_16x16x32_bf16 v[92:95], v[156:159], v[172:175], v[92:95]
	v_mfma_f32_16x16x32_bf16 v[88:91], v[164:167], v[172:175], v[88:91]
	v_mfma_f32_16x16x32_bf16 v[80:83], v[156:159], v[180:183], v[80:83]
	v_mfma_f32_16x16x32_bf16 v[72:75], v[164:167], v[180:183], v[72:75]
	v_mfma_f32_16x16x32_bf16 v[60:63], v[156:159], v[188:191], v[60:63]
	v_mfma_f32_16x16x32_bf16 v[56:59], v[164:167], v[188:191], v[56:59]
	v_mfma_f32_16x16x32_bf16 v[44:47], v[156:159], v[200:203], v[44:47]
	v_mfma_f32_16x16x32_bf16 v[36:39], v[164:167], v[200:203], v[36:39]
	s_setprio 0
	s_barrier
	s_add_u32 s68, s26, 0x80000
	s_addc_u32 s69, s27, 0
	s_add_i32 s33, s60, s30
	v_lshl_add_u64 v[152:153], s[68:69], 0, v[130:131]
	s_mov_b32 m0, s33
	s_nop 0
	global_load_lds_dwordx4 v[152:153], off
	v_lshl_add_u64 v[152:153], s[68:69], 0, v[128:129]
	s_add_i32 m0, s33, 0x2000
	s_nop 0
	global_load_lds_dwordx4 v[152:153], off
	s_cmp_lg_u32 s67, -2
	s_cbranch_scc1 .Lgh_p7_strict
	s_cmp_eq_u32 s99, 0
	s_cbranch_scc1 .Lgh_p7_strict
	s_waitcnt vmcnt(24)
	s_branch .Lgh_p7_join

.Lgh_p7_join:
	s_barrier
	s_setprio 1
	v_mfma_f32_16x16x32_bf16 v[28:31], v[204:207], v[168:171], v[28:31]
	v_mfma_f32_16x16x32_bf16 v[24:27], v[216:219], v[168:171], v[24:27]
	v_mfma_f32_16x16x32_bf16 v[20:23], v[204:207], v[176:179], v[20:23]
	v_mfma_f32_16x16x32_bf16 v[16:19], v[216:219], v[176:179], v[16:19]
	v_mfma_f32_16x16x32_bf16 v[12:15], v[204:207], v[184:187], v[12:15]
	v_mfma_f32_16x16x32_bf16 v[8:11], v[216:219], v[184:187], v[8:11]
	v_mfma_f32_16x16x32_bf16 v[4:7], v[204:207], v[192:195], v[4:7]
	v_mfma_f32_16x16x32_bf16 v[0:3], v[216:219], v[192:195], v[0:3]
	v_mfma_f32_16x16x32_bf16 v[28:31], v[208:211], v[172:175], v[28:31]
	v_mfma_f32_16x16x32_bf16 v[24:27], v[220:223], v[172:175], v[24:27]
	v_mfma_f32_16x16x32_bf16 v[20:23], v[208:211], v[180:183], v[20:23]
	v_mfma_f32_16x16x32_bf16 v[16:19], v[220:223], v[180:183], v[16:19]
	v_mfma_f32_16x16x32_bf16 v[12:15], v[208:211], v[188:191], v[12:15]
	v_mfma_f32_16x16x32_bf16 v[8:11], v[220:223], v[188:191], v[8:11]
	v_mfma_f32_16x16x32_bf16 v[4:7], v[208:211], v[200:203], v[4:7]
	v_mfma_f32_16x16x32_bf16 v[0:3], v[220:223], v[200:203], v[0:3]
	s_setprio 0
	s_add_i32 s33, 0, 0x18000
	v_add_u32_e32 v151, s33, v146
	s_barrier
	ds_read_b128 v[152:155], v151
	ds_read_b128 v[156:159], v151 offset:1024
	ds_read_b128 v[160:163], v151 offset:2048
	ds_read_b128 v[164:167], v151 offset:3072
	s_add_u32 s28, s28, 0x80000
	s_addc_u32 s29, s29, 0
	s_mov_b32 m0, s52
	v_lshl_add_u64 v[204:205], s[28:29], 0, v[134:135]
	ds_read_b128 v[168:171], v149 offset:32768
	ds_read_b128 v[172:175], v149 offset:33792
	ds_read_b128 v[176:179], v149 offset:34816
	ds_read_b128 v[180:183], v149 offset:35840
	ds_read_b128 v[184:187], v149 offset:36864
	ds_read_b128 v[188:191], v149 offset:37888
	ds_read_b128 v[192:195], v149 offset:38912
	ds_read_b128 v[200:203], v149 offset:39936
	global_load_lds_dwordx4 v[204:205], off
	v_lshl_add_u64 v[204:205], s[28:29], 0, v[132:133]
	s_mov_b32 m0, s53
	s_nop 0
	global_load_lds_dwordx4 v[204:205], off
	s_waitcnt lgkmcnt(8)
	s_barrier
	s_waitcnt lgkmcnt(0)
	s_setprio 1
	s_waitcnt lgkmcnt(0)
	v_mfma_f32_16x16x32_bf16 v[124:127], v[152:155], v[168:171], v[124:127]
	v_mfma_f32_16x16x32_bf16 v[120:123], v[160:163], v[168:171], v[120:123]
	v_mfma_f32_16x16x32_bf16 v[116:119], v[152:155], v[176:179], v[116:119]
	v_mfma_f32_16x16x32_bf16 v[112:115], v[160:163], v[176:179], v[112:115]
	v_mfma_f32_16x16x32_bf16 v[108:111], v[152:155], v[184:187], v[108:111]
	v_mfma_f32_16x16x32_bf16 v[104:107], v[160:163], v[184:187], v[104:107]
	v_mfma_f32_16x16x32_bf16 v[100:103], v[152:155], v[192:195], v[100:103]
	v_mfma_f32_16x16x32_bf16 v[96:99], v[160:163], v[192:195], v[96:99]
	v_mfma_f32_16x16x32_bf16 v[124:127], v[156:159], v[172:175], v[124:127]
	v_mfma_f32_16x16x32_bf16 v[120:123], v[164:167], v[172:175], v[120:123]
	v_mfma_f32_16x16x32_bf16 v[116:119], v[156:159], v[180:183], v[116:119]
	v_mfma_f32_16x16x32_bf16 v[112:115], v[164:167], v[180:183], v[112:115]
	v_mfma_f32_16x16x32_bf16 v[108:111], v[156:159], v[188:191], v[108:111]
	v_mfma_f32_16x16x32_bf16 v[104:107], v[164:167], v[188:191], v[104:107]
	v_mfma_f32_16x16x32_bf16 v[100:103], v[156:159], v[200:203], v[100:103]
	v_mfma_f32_16x16x32_bf16 v[96:99], v[164:167], v[200:203], v[96:99]
	s_setprio 0
	s_barrier
	s_add_i32 s28, 0, 0x1c000
	s_add_i32 s29, s33, s30
	v_add_u32_e32 v151, s28, v146
	v_lshl_add_u64 v[196:197], v[196:197], 0, s[10:11]
	s_mov_b32 m0, s29
	ds_read_b128 v[204:207], v151
	ds_read_b128 v[208:211], v151 offset:1024
	ds_read_b128 v[216:219], v151 offset:2048
	ds_read_b128 v[220:223], v151 offset:3072
	global_load_lds_dwordx4 v[196:197], off
	v_lshl_add_u64 v[196:197], v[224:225], 0, s[10:11]
	s_add_i32 m0, s29, 0x2000
	s_nop 0
	global_load_lds_dwordx4 v[196:197], off
	s_barrier
	s_waitcnt lgkmcnt(0)
	s_setprio 1
	s_waitcnt lgkmcnt(0)
	v_mfma_f32_16x16x32_bf16 v[84:87], v[204:207], v[168:171], v[84:87]
	v_mfma_f32_16x16x32_bf16 v[76:79], v[216:219], v[168:171], v[76:79]
	v_mfma_f32_16x16x32_bf16 v[68:71], v[204:207], v[176:179], v[68:71]
	v_mfma_f32_16x16x32_bf16 v[64:67], v[216:219], v[176:179], v[64:67]
	v_mfma_f32_16x16x32_bf16 v[52:55], v[204:207], v[184:187], v[52:55]
	v_mfma_f32_16x16x32_bf16 v[48:51], v[216:219], v[184:187], v[48:51]
	v_mfma_f32_16x16x32_bf16 v[40:43], v[204:207], v[192:195], v[40:43]
	v_mfma_f32_16x16x32_bf16 v[32:35], v[216:219], v[192:195], v[32:35]
	v_mfma_f32_16x16x32_bf16 v[84:87], v[208:211], v[172:175], v[84:87]
	v_mfma_f32_16x16x32_bf16 v[76:79], v[220:223], v[172:175], v[76:79]
	v_mfma_f32_16x16x32_bf16 v[68:71], v[208:211], v[180:183], v[68:71]
	v_mfma_f32_16x16x32_bf16 v[64:67], v[220:223], v[180:183], v[64:67]
	v_mfma_f32_16x16x32_bf16 v[52:55], v[208:211], v[188:191], v[52:55]
	v_mfma_f32_16x16x32_bf16 v[48:51], v[220:223], v[188:191], v[48:51]
	v_mfma_f32_16x16x32_bf16 v[40:43], v[208:211], v[200:203], v[40:43]
	v_mfma_f32_16x16x32_bf16 v[32:35], v[220:223], v[200:203], v[32:35]
	s_setprio 0
	s_mov_b32 m0, s55
	v_lshl_add_u64 v[196:197], v[230:231], 0, s[10:11]
	s_barrier
	ds_read_b128 v[168:171], v149 offset:49152
	ds_read_b128 v[172:175], v149 offset:50176
	ds_read_b128 v[176:179], v149 offset:51200
	ds_read_b128 v[180:183], v149 offset:52224
	ds_read_b128 v[184:187], v149 offset:53248
	ds_read_b128 v[188:191], v149 offset:54272
	ds_read_b128 v[192:195], v149 offset:55296
	ds_read_b128 v[200:203], v149 offset:56320
	global_load_lds_dwordx4 v[196:197], off
	v_lshl_add_u64 v[196:197], v[232:233], 0, s[10:11]
	s_mov_b32 m0, s56
	s_nop 0
	global_load_lds_dwordx4 v[196:197], off
	s_barrier
	s_waitcnt lgkmcnt(0)
	s_setprio 1
	s_waitcnt lgkmcnt(0)
	v_mfma_f32_16x16x32_bf16 v[92:95], v[152:155], v[168:171], v[92:95]
	v_mfma_f32_16x16x32_bf16 v[88:91], v[160:163], v[168:171], v[88:91]
	v_mfma_f32_16x16x32_bf16 v[80:83], v[152:155], v[176:179], v[80:83]
	v_mfma_f32_16x16x32_bf16 v[72:75], v[160:163], v[176:179], v[72:75]
	v_mfma_f32_16x16x32_bf16 v[60:63], v[152:155], v[184:187], v[60:63]
	v_mfma_f32_16x16x32_bf16 v[56:59], v[160:163], v[184:187], v[56:59]
	v_mfma_f32_16x16x32_bf16 v[44:47], v[152:155], v[192:195], v[44:47]
	v_mfma_f32_16x16x32_bf16 v[36:39], v[160:163], v[192:195], v[36:39]
	v_mfma_f32_16x16x32_bf16 v[92:95], v[156:159], v[172:175], v[92:95]
	v_mfma_f32_16x16x32_bf16 v[88:91], v[164:167], v[172:175], v[88:91]
	v_mfma_f32_16x16x32_bf16 v[80:83], v[156:159], v[180:183], v[80:83]
	v_mfma_f32_16x16x32_bf16 v[72:75], v[164:167], v[180:183], v[72:75]
	v_mfma_f32_16x16x32_bf16 v[60:63], v[156:159], v[188:191], v[60:63]
	v_mfma_f32_16x16x32_bf16 v[56:59], v[164:167], v[188:191], v[56:59]
	v_mfma_f32_16x16x32_bf16 v[44:47], v[156:159], v[200:203], v[44:47]
	v_mfma_f32_16x16x32_bf16 v[36:39], v[164:167], v[200:203], v[36:39]
	s_setprio 0
	s_barrier
	s_add_u32 s26, s26, 0x80080
	s_addc_u32 s27, s27, 0
	s_add_i32 s28, s28, s30
	v_lshl_add_u64 v[152:153], s[26:27], 0, v[130:131]
	s_mov_b32 m0, s28
	s_nop 0
	global_load_lds_dwordx4 v[152:153], off
	v_lshl_add_u64 v[152:153], s[26:27], 0, v[128:129]
	s_add_i32 m0, s28, 0x2000
	s_nop 0
	global_load_lds_dwordx4 v[152:153], off
	s_waitcnt vmcnt(6)
	s_barrier
	s_setprio 1
	v_mfma_f32_16x16x32_bf16 v[28:31], v[204:207], v[168:171], v[28:31]
	v_mfma_f32_16x16x32_bf16 v[24:27], v[216:219], v[168:171], v[24:27]
	v_mfma_f32_16x16x32_bf16 v[20:23], v[204:207], v[176:179], v[20:23]
	v_mfma_f32_16x16x32_bf16 v[16:19], v[216:219], v[176:179], v[16:19]
	v_mfma_f32_16x16x32_bf16 v[12:15], v[204:207], v[184:187], v[12:15]
	v_mfma_f32_16x16x32_bf16 v[8:11], v[216:219], v[184:187], v[8:11]
	v_mfma_f32_16x16x32_bf16 v[4:7], v[204:207], v[192:195], v[4:7]
	v_mfma_f32_16x16x32_bf16 v[0:3], v[216:219], v[192:195], v[0:3]
	v_mfma_f32_16x16x32_bf16 v[28:31], v[208:211], v[172:175], v[28:31]
	v_mfma_f32_16x16x32_bf16 v[24:27], v[220:223], v[172:175], v[24:27]
	v_mfma_f32_16x16x32_bf16 v[20:23], v[208:211], v[180:183], v[20:23]
	v_mfma_f32_16x16x32_bf16 v[16:19], v[220:223], v[180:183], v[16:19]
	v_mfma_f32_16x16x32_bf16 v[12:15], v[208:211], v[188:191], v[12:15]
	v_mfma_f32_16x16x32_bf16 v[8:11], v[220:223], v[188:191], v[8:11]
	v_mfma_f32_16x16x32_bf16 v[4:7], v[208:211], v[200:203], v[4:7]
	v_mfma_f32_16x16x32_bf16 v[0:3], v[220:223], v[200:203], v[0:3]
	s_setprio 0
	s_add_i32 s67, s67, 2
	s_add_u32 s24, s24, 0x100
	s_addc_u32 s25, s25, 0
	s_add_u32 s65, s65, 0x100
	s_addc_u32 s66, s66, 0
	s_cmp_gt_u32 s67, 29
	s_barrier
	s_cbranch_scc0 .LBB0_820
	s_add_u32 s100, s63, 0x80080
	s_addc_u32 s101, s19, 0
	s_mov_b32 s99, 1
	v_lshl_add_u64 v[196:197], s[100:101], 0, v[136:137]
	s_add_i32 m0, s13, 0xc000
	s_nop 0
	global_load_lds_dwordx4 v[196:197], off
	v_lshl_add_u64 v[196:197], s[100:101], 0, v[138:139]
	s_add_i32 m0, s13, 0xe000
	s_nop 0
	global_load_lds_dwordx4 v[196:197], off
	v_lshl_or_b32 v152, s62, 8, v147
	v_lshl_add_u32 v151, s12, 8, v145
	v_ashrrev_i32_e32 v153, 31, v152
	v_cvt_pk_bf16_f32 v124, v124, v125
	v_cvt_pk_bf16_f32 v125, v126, v127
	v_cvt_pk_bf16_f32 v126, v120, v121
	v_mov_b64_e32 v[120:121], s[8:9]
	v_cvt_pk_bf16_f32 v127, v122, v123
	v_mad_i64_i32 v[122:123], s[24:25], v151, s61, v[120:121]
	v_lshlrev_b64 v[152:153], 1, v[152:153]
	v_lshl_add_u64 v[122:123], v[122:123], 0, v[152:153]
	v_cvt_pk_bf16_f32 v60, v60, v61
	v_cvt_pk_bf16_f32 v61, v62, v63
	v_cvt_pk_bf16_f32 v63, v58, v59
	v_add_u32_e32 v58, 0xb0, v151
	global_store_dwordx4 v[122:123], v[124:127], off sc1
	v_cvt_pk_bf16_f32 v44, v44, v45
	v_cvt_pk_bf16_f32 v45, v46, v47
	v_or_b32_e32 v124, 16, v151
	v_cvt_pk_bf16_f32 v46, v36, v37
	v_mad_i64_i32 v[36:37], s[24:25], v58, s61, v[120:121]
	v_cvt_pk_bf16_f32 v116, v116, v117
	v_cvt_pk_bf16_f32 v117, v118, v119
	v_cvt_pk_bf16_f32 v118, v112, v113
	v_cvt_pk_bf16_f32 v119, v114, v115
	v_mad_i64_i32 v[112:113], s[24:25], v124, s61, v[120:121]
	v_or_b32_e32 v114, 32, v151
	v_cvt_pk_bf16_f32 v47, v38, v39
	v_lshl_add_u64 v[58:59], v[36:37], 0, v[152:153]
	v_cvt_pk_bf16_f32 v36, v84, v85
	v_cvt_pk_bf16_f32 v37, v86, v87
	v_cvt_pk_bf16_f32 v38, v76, v77
	v_cvt_pk_bf16_f32 v39, v78, v79
	v_lshl_add_u64 v[112:113], v[112:113], 0, v[152:153]
	v_cvt_pk_bf16_f32 v108, v108, v109
	v_cvt_pk_bf16_f32 v109, v110, v111
	v_cvt_pk_bf16_f32 v110, v104, v105
	v_cvt_pk_bf16_f32 v111, v106, v107
	v_mad_i64_i32 v[104:105], s[24:25], v114, s61, v[120:121]
	v_or_b32_e32 v106, 48, v151
	v_cvt_pk_bf16_f32 v100, v100, v101
	v_cvt_pk_bf16_f32 v101, v102, v103
	v_cvt_pk_bf16_f32 v103, v98, v99
	v_add_u32_e32 v98, 0x80, v151
	v_cvt_pk_bf16_f32 v92, v92, v93
	v_cvt_pk_bf16_f32 v93, v94, v95
	v_cvt_pk_bf16_f32 v95, v90, v91
	v_add_u32_e32 v90, 0x90, v151
	v_cvt_pk_bf16_f32 v80, v80, v81
	v_cvt_pk_bf16_f32 v81, v82, v83
	v_cvt_pk_bf16_f32 v83, v74, v75
	v_add_u32_e32 v74, 0xa0, v151
	global_store_dwordx4 v[122:123], v[36:39], off offset:256 sc1
	v_lshl_add_u64 v[104:105], v[104:105], 0, v[152:153]
	v_cvt_pk_bf16_f32 v102, v96, v97
	v_cvt_pk_bf16_f32 v36, v68, v69
	v_cvt_pk_bf16_f32 v37, v70, v71
	v_cvt_pk_bf16_f32 v38, v64, v65
	v_cvt_pk_bf16_f32 v39, v66, v67
	v_mad_i64_i32 v[96:97], s[24:25], v106, s61, v[120:121]
	v_cvt_pk_bf16_f32 v94, v88, v89
	v_mad_i64_i32 v[88:89], s[24:25], v98, s61, v[120:121]
	v_cvt_pk_bf16_f32 v82, v72, v73
	v_mad_i64_i32 v[72:73], s[24:25], v90, s61, v[120:121]
	v_cvt_pk_bf16_f32 v62, v56, v57
	v_mad_i64_i32 v[56:57], s[24:25], v74, s61, v[120:121]
	global_store_dwordx4 v[112:113], v[36:39], off offset:256 sc1
	v_lshl_add_u64 v[96:97], v[96:97], 0, v[152:153]
	v_lshl_add_u64 v[88:89], v[88:89], 0, v[152:153]
	v_cvt_pk_bf16_f32 v36, v52, v53
	v_cvt_pk_bf16_f32 v37, v54, v55
	v_cvt_pk_bf16_f32 v38, v48, v49
	v_cvt_pk_bf16_f32 v39, v50, v51
	v_lshl_add_u64 v[72:73], v[72:73], 0, v[152:153]
	v_lshl_add_u64 v[56:57], v[56:57], 0, v[152:153]
	global_store_dwordx4 v[104:105], v[36:39], off offset:256 sc1
	v_cvt_pk_bf16_f32 v28, v28, v29
	v_cvt_pk_bf16_f32 v29, v30, v31
	v_cvt_pk_bf16_f32 v36, v40, v41
	v_cvt_pk_bf16_f32 v37, v42, v43
	v_cvt_pk_bf16_f32 v38, v32, v33
	v_cvt_pk_bf16_f32 v39, v34, v35
	v_cvt_pk_bf16_f32 v30, v24, v25
	v_cvt_pk_bf16_f32 v31, v26, v27
	v_cvt_pk_bf16_f32 v20, v20, v21
	v_cvt_pk_bf16_f32 v21, v22, v23
	v_cvt_pk_bf16_f32 v22, v16, v17
	v_cvt_pk_bf16_f32 v23, v18, v19
	v_cvt_pk_bf16_f32 v12, v12, v13
	v_cvt_pk_bf16_f32 v13, v14, v15
	v_cvt_pk_bf16_f32 v14, v8, v9
	v_cvt_pk_bf16_f32 v15, v10, v11
	v_cvt_pk_bf16_f32 v4, v4, v5
	v_cvt_pk_bf16_f32 v5, v6, v7
	v_cvt_pk_bf16_f32 v6, v0, v1
	v_cvt_pk_bf16_f32 v7, v2, v3
	s_and_b64 vcc, exec, s[6:7]
	s_mov_b32 s12, s18
	s_mov_b32 s62, s14
	s_mov_b64 s[26:27], s[22:23]
	s_mov_b64 s[24:25], s[20:21]
	global_store_dwordx4 v[112:113], v[116:119], off sc1
	global_store_dwordx4 v[104:105], v[108:111], off sc1
	global_store_dwordx4 v[96:97], v[100:103], off sc1
	global_store_dwordx4 v[88:89], v[92:95], off sc1
	global_store_dwordx4 v[72:73], v[80:83], off sc1
	global_store_dwordx4 v[56:57], v[60:63], off sc1
	global_store_dwordx4 v[58:59], v[44:47], off sc1
	global_store_dwordx4 v[96:97], v[36:39], off offset:256 sc1
	global_store_dwordx4 v[88:89], v[28:31], off offset:256 sc1
	global_store_dwordx4 v[72:73], v[20:23], off offset:256 sc1
	global_store_dwordx4 v[56:57], v[12:15], off offset:256 sc1
	global_store_dwordx4 v[58:59], v[4:7], off offset:256 sc1
	s_cbranch_vccz .LBB0_817
	s_waitcnt vmcnt(0)
	s_cmpk_gt_u32 s3, 0xff
	s_cbranch_scc1 .LBB0_824
	s_barrier

.LBB0_1030:
	s_mov_b32 s99, 0
	s_cmp_lt_i32 s44, 10
	s_cselect_b64 s[8:9], -1, 0
	s_and_b64 s[10:11], s[8:9], s[6:7]
	s_andn2_b64 vcc, exec, s[10:11]
	s_cbranch_vccnz .LBB0_1163
	s_ashr_i32 s3, s2, 31
	s_cmpk_gt_i32 s2, 0x23f
	s_cselect_b64 s[6:7], -1, 0
	s_add_u32 s12, s42, 0x14804000
	s_addc_u32 s13, s43, 0
	s_add_u32 s14, s42, 0x3904000
	s_addc_u32 s15, s43, 0
	s_add_u32 s16, s42, 0x1e804000
	s_addc_u32 s17, s43, 0
	s_lshr_b32 s8, s3, 29
	s_add_i32 s8, s2, s8
	s_ashr_i32 s9, s8, 3
	s_and_b32 s8, s8, -8
	s_sub_i32 s8, s2, s8
	s_cmp_lt_i32 s8, 0
	s_movk_i32 s18, 0x49
	s_cselect_b32 s18, s18, 0x48
	s_mul_i32 s8, s18, s8
	s_add_i32 s9, s8, s9
	s_mul_hi_i32 s8, s9, 0x38e38e39
	s_lshr_b32 s18, s8, 31
	s_ashr_i32 s8, s8, 4
	s_add_i32 s8, s8, s18
	s_mul_i32 s18, s8, 0x48
	s_sub_i32 s18, s9, s18
	s_bfe_i32 s9, s18, 0x80000
	s_bfe_u32 s9, s9, 0x3000c
	s_add_i32 s19, s18, s9
	s_bfe_i32 s9, s19, 0x80000
	s_sext_i32_i16 s9, s9
	s_lshr_b32 s9, s9, 3
	s_mov_b32 s90, 4
	s_cmpk_lt_i32 s2, 0x240
	v_readfirstlane_b32 s70, v213
	s_cbranch_scc1 .LBB0_1033
	s_add_u32 s34, s2, 0xfffffdc0
	s_addc_u32 s35, s3, -1
	s_branch .LBB0_1034

.LBB0_1057:
	ds_read_b128 v[150:153], v163
	ds_read_b128 v[168:171], v163 offset:1024
	ds_read_b128 v[172:175], v163 offset:2048
	ds_read_b128 v[176:179], v163 offset:3072
	s_add_u32 s33, s64, 0xfffe0080
	s_addc_u32 s68, s65, -1
	s_cmp_eq_u32 s93, 4
	s_cselect_b64 s[94:95], -1, 0
	s_and_b64 s[66:67], s[94:95], exec
	s_cselect_b32 s69, s9, s68
	s_cselect_b32 s68, s37, s33
	s_cselect_b32 s67, s35, s92
	s_cselect_b32 s66, s63, s91
	s_and_b64 vcc, s[6:7], s[94:95]
	v_cndmask_b32_e32 v132, v147, v166, vcc
	v_lshl_add_u64 v[148:149], s[64:65], 0, v[136:137]
	s_add_i32 m0, s73, 0xc000
	ds_read_b128 v[180:183], v164
	ds_read_b128 v[184:187], v164 offset:1024
	ds_read_b128 v[188:191], v164 offset:2048
	ds_read_b128 v[192:195], v164 offset:3072
	ds_read_b128 v[200:203], v164 offset:4096
	ds_read_b128 v[204:207], v164 offset:5120
	ds_read_b128 v[208:211], v164 offset:6144
	ds_read_b128 v[216:219], v164 offset:7168
	global_load_lds_dwordx4 v[148:149], off
	v_lshl_add_u64 v[148:149], s[64:65], 0, v[138:139]
	s_add_i32 m0, s73, 0xe000
	s_nop 0
	global_load_lds_dwordx4 v[148:149], off
	s_waitcnt lgkmcnt(8)
	s_barrier
	s_waitcnt lgkmcnt(0)
	v_cndmask_b32_e32 v148, v146, v167, vcc
	s_setprio 1
	s_waitcnt lgkmcnt(0)
	v_mfma_f32_16x16x32_bf16 v[124:127], v[150:153], v[180:183], v[124:127]
	v_mfma_f32_16x16x32_bf16 v[120:123], v[172:175], v[180:183], v[120:123]
	v_mfma_f32_16x16x32_bf16 v[116:119], v[150:153], v[188:191], v[116:119]
	v_mfma_f32_16x16x32_bf16 v[112:115], v[172:175], v[188:191], v[112:115]
	v_mfma_f32_16x16x32_bf16 v[108:111], v[150:153], v[200:203], v[108:111]
	v_mfma_f32_16x16x32_bf16 v[104:107], v[172:175], v[200:203], v[104:107]
	v_mfma_f32_16x16x32_bf16 v[100:103], v[150:153], v[208:211], v[100:103]
	v_mfma_f32_16x16x32_bf16 v[96:99], v[172:175], v[208:211], v[96:99]
	v_mfma_f32_16x16x32_bf16 v[124:127], v[168:171], v[184:187], v[124:127]
	v_mfma_f32_16x16x32_bf16 v[120:123], v[176:179], v[184:187], v[120:123]
	v_mfma_f32_16x16x32_bf16 v[116:119], v[168:171], v[192:195], v[116:119]
	v_mfma_f32_16x16x32_bf16 v[112:115], v[176:179], v[192:195], v[112:115]
	v_mfma_f32_16x16x32_bf16 v[108:111], v[168:171], v[204:207], v[108:111]
	v_mfma_f32_16x16x32_bf16 v[104:107], v[176:179], v[204:207], v[104:107]
	v_mfma_f32_16x16x32_bf16 v[100:103], v[168:171], v[216:219], v[100:103]
	v_mfma_f32_16x16x32_bf16 v[96:99], v[176:179], v[216:219], v[96:99]
	s_setprio 0
	s_barrier
	s_add_i32 s33, s85, s72
	s_mov_b32 m0, s33
	ds_read_b128 v[220:223], v165
	ds_read_b128 v[230:233], v165 offset:1024
	ds_read_b128 v[234:237], v165 offset:2048
	ds_read_b128 v[238:241], v165 offset:3072
	global_load_lds_dwordx4 v132, s[66:67]
	s_add_i32 m0, s33, 0x2000
	v_mov_b32_e32 v149, v133
	global_load_lds_dwordx4 v148, s[66:67]
	s_barrier
	s_waitcnt lgkmcnt(0)
	v_lshl_add_u64 v[154:155], s[66:67], 0, v[132:133]
	v_lshl_add_u64 v[196:197], s[66:67], 0, v[148:149]
	s_setprio 1
	s_waitcnt lgkmcnt(0)
	v_mfma_f32_16x16x32_bf16 v[60:63], v[220:223], v[180:183], v[60:63]
	v_mfma_f32_16x16x32_bf16 v[56:59], v[234:237], v[180:183], v[56:59]
	v_mfma_f32_16x16x32_bf16 v[52:55], v[220:223], v[188:191], v[52:55]
	v_mfma_f32_16x16x32_bf16 v[48:51], v[234:237], v[188:191], v[48:51]
	v_mfma_f32_16x16x32_bf16 v[44:47], v[220:223], v[200:203], v[44:47]
	v_mfma_f32_16x16x32_bf16 v[40:43], v[234:237], v[200:203], v[40:43]
	v_mfma_f32_16x16x32_bf16 v[36:39], v[220:223], v[208:211], v[36:39]
	v_mfma_f32_16x16x32_bf16 v[32:35], v[234:237], v[208:211], v[32:35]
	v_mfma_f32_16x16x32_bf16 v[60:63], v[230:233], v[184:187], v[60:63]
	v_mfma_f32_16x16x32_bf16 v[56:59], v[238:241], v[184:187], v[56:59]
	v_mfma_f32_16x16x32_bf16 v[52:55], v[230:233], v[192:195], v[52:55]
	v_mfma_f32_16x16x32_bf16 v[48:51], v[238:241], v[192:195], v[48:51]
	v_mfma_f32_16x16x32_bf16 v[44:47], v[230:233], v[204:207], v[44:47]
	v_mfma_f32_16x16x32_bf16 v[40:43], v[238:241], v[204:207], v[40:43]
	v_mfma_f32_16x16x32_bf16 v[36:39], v[230:233], v[216:219], v[36:39]
	v_mfma_f32_16x16x32_bf16 v[32:35], v[238:241], v[216:219], v[32:35]
	s_setprio 0
	s_mov_b32 m0, s73
	v_lshl_add_u64 v[224:225], s[68:69], 0, v[128:129]
	s_barrier
	ds_read_b128 v[180:183], v164 offset:16384
	ds_read_b128 v[184:187], v164 offset:17408
	ds_read_b128 v[188:191], v164 offset:18432
	ds_read_b128 v[192:195], v164 offset:19456
	ds_read_b128 v[200:203], v164 offset:20480
	ds_read_b128 v[204:207], v164 offset:21504
	ds_read_b128 v[208:211], v164 offset:22528
	ds_read_b128 v[216:219], v164 offset:23552
	global_load_lds_dwordx4 v[224:225], off
	v_lshl_add_u64 v[242:243], s[68:69], 0, v[130:131]
	s_mov_b32 m0, s74
	s_nop 0
	global_load_lds_dwordx4 v[242:243], off
	s_barrier
	s_waitcnt lgkmcnt(0)
	s_setprio 1
	s_waitcnt lgkmcnt(0)
	v_mfma_f32_16x16x32_bf16 v[92:95], v[150:153], v[180:183], v[92:95]
	v_mfma_f32_16x16x32_bf16 v[88:91], v[172:175], v[180:183], v[88:91]
	v_mfma_f32_16x16x32_bf16 v[84:87], v[150:153], v[188:191], v[84:87]
	v_mfma_f32_16x16x32_bf16 v[80:83], v[172:175], v[188:191], v[80:83]
	v_mfma_f32_16x16x32_bf16 v[76:79], v[150:153], v[200:203], v[76:79]
	v_mfma_f32_16x16x32_bf16 v[72:75], v[172:175], v[200:203], v[72:75]
	v_mfma_f32_16x16x32_bf16 v[68:71], v[150:153], v[208:211], v[68:71]
	v_mfma_f32_16x16x32_bf16 v[64:67], v[172:175], v[208:211], v[64:67]
	v_mfma_f32_16x16x32_bf16 v[92:95], v[168:171], v[184:187], v[92:95]
	v_mfma_f32_16x16x32_bf16 v[88:91], v[176:179], v[184:187], v[88:91]
	v_mfma_f32_16x16x32_bf16 v[84:87], v[168:171], v[192:195], v[84:87]
	v_mfma_f32_16x16x32_bf16 v[80:83], v[176:179], v[192:195], v[80:83]
	v_mfma_f32_16x16x32_bf16 v[76:79], v[168:171], v[204:207], v[76:79]
	v_mfma_f32_16x16x32_bf16 v[72:75], v[176:179], v[204:207], v[72:75]
	v_mfma_f32_16x16x32_bf16 v[68:71], v[168:171], v[216:219], v[68:71]
	v_mfma_f32_16x16x32_bf16 v[64:67], v[176:179], v[216:219], v[64:67]
	s_setprio 0
	s_barrier
	s_add_u32 s94, s66, 0x20000
	s_addc_u32 s95, s67, 0
	s_add_i32 s33, s86, s72
	s_mov_b32 m0, s33
	s_nop 0
	global_load_lds_dwordx4 v132, s[94:95]
	s_add_i32 m0, s33, 0x2000
	s_nop 0
	global_load_lds_dwordx4 v148, s[94:95]
	s_cmp_lg_u32 s93, -2
	s_cbranch_scc1 .Lgh_p9_strict
	s_cmp_eq_u32 s99, 0
	s_cbranch_scc1 .Lgh_p9_strict
	s_waitcnt vmcnt(24)
	s_branch .Lgh_p9_join

.Lgh_p9_join:
	s_barrier
	s_setprio 1
	v_mfma_f32_16x16x32_bf16 v[28:31], v[220:223], v[180:183], v[28:31]
	v_mfma_f32_16x16x32_bf16 v[24:27], v[234:237], v[180:183], v[24:27]
	v_mfma_f32_16x16x32_bf16 v[20:23], v[220:223], v[188:191], v[20:23]
	v_mfma_f32_16x16x32_bf16 v[16:19], v[234:237], v[188:191], v[16:19]
	v_mfma_f32_16x16x32_bf16 v[12:15], v[220:223], v[200:203], v[12:15]
	v_mfma_f32_16x16x32_bf16 v[8:11], v[234:237], v[200:203], v[8:11]
	v_mfma_f32_16x16x32_bf16 v[4:7], v[220:223], v[208:211], v[4:7]
	v_mfma_f32_16x16x32_bf16 v[0:3], v[234:237], v[208:211], v[0:3]
	v_mfma_f32_16x16x32_bf16 v[28:31], v[230:233], v[184:187], v[28:31]
	v_mfma_f32_16x16x32_bf16 v[24:27], v[238:241], v[184:187], v[24:27]
	v_mfma_f32_16x16x32_bf16 v[20:23], v[230:233], v[192:195], v[20:23]
	v_mfma_f32_16x16x32_bf16 v[16:19], v[238:241], v[192:195], v[16:19]
	v_mfma_f32_16x16x32_bf16 v[12:15], v[230:233], v[204:207], v[12:15]
	v_mfma_f32_16x16x32_bf16 v[8:11], v[238:241], v[204:207], v[8:11]
	v_mfma_f32_16x16x32_bf16 v[4:7], v[230:233], v[216:219], v[4:7]
	v_mfma_f32_16x16x32_bf16 v[0:3], v[238:241], v[216:219], v[0:3]
	s_setprio 0
	s_add_i32 s33, 0, 0x18000
	v_add_u32_e32 v149, s33, v161
	s_barrier
	ds_read_b128 v[150:153], v149
	ds_read_b128 v[168:171], v149 offset:1024
	ds_read_b128 v[172:175], v149 offset:2048
	ds_read_b128 v[176:179], v149 offset:3072
	s_add_u32 s68, s68, 0x20000
	s_addc_u32 s69, s69, 0
	s_mov_b32 m0, s75
	v_lshl_add_u64 v[220:221], s[68:69], 0, v[128:129]
	ds_read_b128 v[180:183], v164 offset:32768
	ds_read_b128 v[184:187], v164 offset:33792
	ds_read_b128 v[188:191], v164 offset:34816
	ds_read_b128 v[192:195], v164 offset:35840
	ds_read_b128 v[200:203], v164 offset:36864
	ds_read_b128 v[204:207], v164 offset:37888
	ds_read_b128 v[208:211], v164 offset:38912
	ds_read_b128 v[216:219], v164 offset:39936
	global_load_lds_dwordx4 v[220:221], off
	v_lshl_add_u64 v[220:221], s[68:69], 0, v[130:131]
	s_mov_b32 m0, s76
	s_nop 0
	global_load_lds_dwordx4 v[220:221], off
	s_waitcnt lgkmcnt(8)
	s_barrier
	s_waitcnt lgkmcnt(0)
	s_setprio 1
	s_waitcnt lgkmcnt(0)
	v_mfma_f32_16x16x32_bf16 v[124:127], v[150:153], v[180:183], v[124:127]
	v_mfma_f32_16x16x32_bf16 v[120:123], v[172:175], v[180:183], v[120:123]
	v_mfma_f32_16x16x32_bf16 v[116:119], v[150:153], v[188:191], v[116:119]
	v_mfma_f32_16x16x32_bf16 v[112:115], v[172:175], v[188:191], v[112:115]
	v_mfma_f32_16x16x32_bf16 v[108:111], v[150:153], v[200:203], v[108:111]
	v_mfma_f32_16x16x32_bf16 v[104:107], v[172:175], v[200:203], v[104:107]
	v_mfma_f32_16x16x32_bf16 v[100:103], v[150:153], v[208:211], v[100:103]
	v_mfma_f32_16x16x32_bf16 v[96:99], v[172:175], v[208:211], v[96:99]
	v_mfma_f32_16x16x32_bf16 v[124:127], v[168:171], v[184:187], v[124:127]
	v_mfma_f32_16x16x32_bf16 v[120:123], v[176:179], v[184:187], v[120:123]
	v_mfma_f32_16x16x32_bf16 v[116:119], v[168:171], v[192:195], v[116:119]
	v_mfma_f32_16x16x32_bf16 v[112:115], v[176:179], v[192:195], v[112:115]
	v_mfma_f32_16x16x32_bf16 v[108:111], v[168:171], v[204:207], v[108:111]
	v_mfma_f32_16x16x32_bf16 v[104:107], v[176:179], v[204:207], v[104:107]
	v_mfma_f32_16x16x32_bf16 v[100:103], v[168:171], v[216:219], v[100:103]
	v_mfma_f32_16x16x32_bf16 v[96:99], v[176:179], v[216:219], v[96:99]
	s_setprio 0
	s_barrier
	s_add_i32 s68, 0, 0x1c000
	s_add_i32 s33, s33, s72
	v_add_u32_e32 v149, s68, v161
	v_lshl_add_u64 v[154:155], v[154:155], 0, s[30:31]
	s_mov_b32 m0, s33
	ds_read_b128 v[220:223], v149
	ds_read_b128 v[230:233], v149 offset:1024
	ds_read_b128 v[234:237], v149 offset:2048
	ds_read_b128 v[238:241], v149 offset:3072
	global_load_lds_dwordx4 v[154:155], off
	v_lshl_add_u64 v[154:155], v[196:197], 0, s[30:31]
	s_add_i32 m0, s33, 0x2000
	s_nop 0
	global_load_lds_dwordx4 v[154:155], off
	s_barrier
	s_waitcnt lgkmcnt(0)
	s_setprio 1
	s_waitcnt lgkmcnt(0)
	v_mfma_f32_16x16x32_bf16 v[60:63], v[220:223], v[180:183], v[60:63]
	v_mfma_f32_16x16x32_bf16 v[56:59], v[234:237], v[180:183], v[56:59]
	v_mfma_f32_16x16x32_bf16 v[52:55], v[220:223], v[188:191], v[52:55]
	v_mfma_f32_16x16x32_bf16 v[48:51], v[234:237], v[188:191], v[48:51]
	v_mfma_f32_16x16x32_bf16 v[44:47], v[220:223], v[200:203], v[44:47]
	v_mfma_f32_16x16x32_bf16 v[40:43], v[234:237], v[200:203], v[40:43]
	v_mfma_f32_16x16x32_bf16 v[36:39], v[220:223], v[208:211], v[36:39]
	v_mfma_f32_16x16x32_bf16 v[32:35], v[234:237], v[208:211], v[32:35]
	v_mfma_f32_16x16x32_bf16 v[60:63], v[230:233], v[184:187], v[60:63]
	v_mfma_f32_16x16x32_bf16 v[56:59], v[238:241], v[184:187], v[56:59]
	v_mfma_f32_16x16x32_bf16 v[52:55], v[230:233], v[192:195], v[52:55]
	v_mfma_f32_16x16x32_bf16 v[48:51], v[238:241], v[192:195], v[48:51]
	v_mfma_f32_16x16x32_bf16 v[44:47], v[230:233], v[204:207], v[44:47]
	v_mfma_f32_16x16x32_bf16 v[40:43], v[238:241], v[204:207], v[40:43]
	v_mfma_f32_16x16x32_bf16 v[36:39], v[230:233], v[216:219], v[36:39]
	v_mfma_f32_16x16x32_bf16 v[32:35], v[238:241], v[216:219], v[32:35]
	s_setprio 0
	s_mov_b32 m0, s79
	v_lshl_add_u64 v[154:155], v[224:225], 0, s[30:31]
	s_barrier
	ds_read_b128 v[180:183], v164 offset:49152
	ds_read_b128 v[184:187], v164 offset:50176
	ds_read_b128 v[188:191], v164 offset:51200
	ds_read_b128 v[192:195], v164 offset:52224
	ds_read_b128 v[200:203], v164 offset:53248
	ds_read_b128 v[204:207], v164 offset:54272
	ds_read_b128 v[208:211], v164 offset:55296
	ds_read_b128 v[216:219], v164 offset:56320
	global_load_lds_dwordx4 v[154:155], off
	v_lshl_add_u64 v[154:155], v[242:243], 0, s[30:31]
	s_mov_b32 m0, s80
	s_nop 0
	global_load_lds_dwordx4 v[154:155], off
	s_barrier
	s_waitcnt lgkmcnt(0)
	s_setprio 1
	s_waitcnt lgkmcnt(0)
	v_mfma_f32_16x16x32_bf16 v[92:95], v[150:153], v[180:183], v[92:95]
	v_mfma_f32_16x16x32_bf16 v[88:91], v[172:175], v[180:183], v[88:91]
	v_mfma_f32_16x16x32_bf16 v[84:87], v[150:153], v[188:191], v[84:87]
	v_mfma_f32_16x16x32_bf16 v[80:83], v[172:175], v[188:191], v[80:83]
	v_mfma_f32_16x16x32_bf16 v[76:79], v[150:153], v[200:203], v[76:79]
	v_mfma_f32_16x16x32_bf16 v[72:75], v[172:175], v[200:203], v[72:75]
	v_mfma_f32_16x16x32_bf16 v[68:71], v[150:153], v[208:211], v[68:71]
	v_mfma_f32_16x16x32_bf16 v[64:67], v[172:175], v[208:211], v[64:67]
	v_mfma_f32_16x16x32_bf16 v[92:95], v[168:171], v[184:187], v[92:95]
	v_mfma_f32_16x16x32_bf16 v[88:91], v[176:179], v[184:187], v[88:91]
	v_mfma_f32_16x16x32_bf16 v[84:87], v[168:171], v[192:195], v[84:87]
	v_mfma_f32_16x16x32_bf16 v[80:83], v[176:179], v[192:195], v[80:83]
	v_mfma_f32_16x16x32_bf16 v[76:79], v[168:171], v[204:207], v[76:79]
	v_mfma_f32_16x16x32_bf16 v[72:75], v[176:179], v[204:207], v[72:75]
	v_mfma_f32_16x16x32_bf16 v[68:71], v[168:171], v[216:219], v[68:71]
	v_mfma_f32_16x16x32_bf16 v[64:67], v[176:179], v[216:219], v[64:67]
	s_setprio 0
	s_barrier
	s_add_u32 s66, s66, 0x20080
	s_addc_u32 s67, s67, 0
	s_add_i32 s33, s68, s72
	s_mov_b32 m0, s33
	s_nop 0
	global_load_lds_dwordx4 v132, s[66:67]
	s_add_i32 m0, s33, 0x2000
	s_nop 0
	global_load_lds_dwordx4 v148, s[66:67]
	s_waitcnt vmcnt(6)
	s_barrier
	s_setprio 1
	v_mfma_f32_16x16x32_bf16 v[28:31], v[220:223], v[180:183], v[28:31]
	v_mfma_f32_16x16x32_bf16 v[24:27], v[234:237], v[180:183], v[24:27]
	v_mfma_f32_16x16x32_bf16 v[20:23], v[220:223], v[188:191], v[20:23]
	v_mfma_f32_16x16x32_bf16 v[16:19], v[234:237], v[188:191], v[16:19]
	v_mfma_f32_16x16x32_bf16 v[12:15], v[220:223], v[200:203], v[12:15]
	v_mfma_f32_16x16x32_bf16 v[8:11], v[234:237], v[200:203], v[8:11]
	v_mfma_f32_16x16x32_bf16 v[4:7], v[220:223], v[208:211], v[4:7]
	v_mfma_f32_16x16x32_bf16 v[0:3], v[234:237], v[208:211], v[0:3]
	v_mfma_f32_16x16x32_bf16 v[28:31], v[230:233], v[184:187], v[28:31]
	v_mfma_f32_16x16x32_bf16 v[24:27], v[238:241], v[184:187], v[24:27]
	v_mfma_f32_16x16x32_bf16 v[20:23], v[230:233], v[192:195], v[20:23]
	v_mfma_f32_16x16x32_bf16 v[16:19], v[238:241], v[192:195], v[16:19]
	v_mfma_f32_16x16x32_bf16 v[12:15], v[230:233], v[204:207], v[12:15]
	v_mfma_f32_16x16x32_bf16 v[8:11], v[238:241], v[204:207], v[8:11]
	v_mfma_f32_16x16x32_bf16 v[4:7], v[230:233], v[216:219], v[4:7]
	v_mfma_f32_16x16x32_bf16 v[0:3], v[238:241], v[216:219], v[0:3]
	s_setprio 0
	s_add_i32 s93, s93, 2
	s_add_u32 s64, s64, 0x100
	s_addc_u32 s65, s65, 0
	s_add_u32 s91, s91, 0x100
	s_addc_u32 s92, s92, 0
	s_cmp_gt_u32 s93, 5
	s_barrier
	s_cbranch_scc0 .LBB0_1057
	s_add_u32 s100, s37, 0x20080
	s_addc_u32 s101, s9, 0
	s_mov_b32 s99, 1
	v_lshl_add_u64 v[148:149], s[100:101], 0, v[136:137]
	s_add_i32 m0, s73, 0xc000
	s_nop 0
	global_load_lds_dwordx4 v[148:149], off
	v_lshl_add_u64 v[148:149], s[100:101], 0, v[138:139]
	s_add_i32 m0, s73, 0xe000
	s_nop 0
	global_load_lds_dwordx4 v[148:149], off
	s_lshl_b32 s35, s62, 8
	s_and_b32 s6, s90, 4
	s_bitcmp1_b32 s90, 2
	s_cselect_b64 s[64:65], -1, 0
	s_cmp_eq_u32 s6, 0
	v_or_b32_e32 v154, s35, v162
	s_cbranch_scc1 .LBB0_1060
	v_mul_hi_i32 v132, v154, s84
	v_lshrrev_b32_e32 v146, 31, v132
	v_lshrrev_b32_e32 v132, 5, v132
	v_add_u32_e32 v132, v132, v146
	v_mul_lo_u32 v132, v132, s82
	v_sub_u32_e32 v132, v154, v132
	v_add_u32_e32 v146, 0xffffff80, v132
	v_lshrrev_b32_e32 v146, 1, v146
	v_cmp_lt_i32_e32 vcc, s87, v132
	s_and_b64 s[66:67], vcc, exec
	s_nop 0
	v_cndmask_b32_e32 v132, 0, v146, vcc
	v_mov_b64_e32 v[148:149], v[132:133]
	s_branch .LBB0_1061

.LBB0_1417:
	s_mov_b32 s99, 0
	s_cmp_lt_i32 s44, 12
	s_cselect_b64 s[8:9], -1, 0
	s_and_b64 s[8:9], s[8:9], s[6:7]
	s_andn2_b64 vcc, exec, s[8:9]
	s_cbranch_vccnz .LBB0_1434
	s_cmpk_gt_i32 s2, 0x1ff
	v_readfirstlane_b32 s3, v213
	s_cbranch_scc1 .LBB0_1434
	v_lshrrev_b32_e32 v2, 1, v213
	v_and_b32_e32 v2, 24, v2
	v_and_b32_e32 v3, 4, v198
	v_bfe_u32 v4, v213, 2, 2
	v_lshlrev_b32_e32 v0, 4, v213
	v_and_b32_e32 v1, 32, v213
	v_bfe_u32 v10, v213, 2, 4
	v_or3_b32 v2, v3, v4, v2
	v_lshrrev_b32_e32 v3, 3, v213
	s_movk_i32 s6, 0x70
	s_add_u32 s48, s42, 0x5004000
	v_bitop3_b32 v8, v0, v1, 48 bitop3:0x6c
	v_and_b32_e32 v9, 64, v213
	v_and_or_b32 v4, v3, s6, v10
	s_movk_i32 s6, 0x60
	v_add_u32_e32 v11, 0x2000, v0
	s_addc_u32 s49, s43, 0
	v_or_b32_e32 v1, v8, v9
	v_and_or_b32 v3, v3, s6, v2
	v_lshrrev_b32_e32 v0, 7, v11
	s_movk_i32 s6, 0xf0
	s_add_u32 s50, s42, 0x3b44000
	v_lshl_or_b32 v130, v3, 12, v1
	v_and_or_b32 v3, v0, s6, v10
	s_movk_i32 s6, 0xe0
	s_addc_u32 s51, s43, 0
	s_ashr_i32 s53, s2, 31
	v_and_or_b32 v0, v0, s6, v2
	s_lshr_b32 s6, s53, 29
	s_add_i32 s6, s2, s6
	s_ashr_i32 s10, s6, 3
	s_and_b32 s6, s6, -8
	s_lshr_b32 s14, s3, 6
	s_sub_i32 s6, s2, s6
	s_lshr_b32 s7, s3, 8
	s_lshl_b32 s52, s14, 10
	s_lshl_b32 s12, s6, 6
	s_mul_i32 s11, s6, 0x41
	s_cmp_lt_i32 s6, 0
	s_cselect_b32 s6, s11, s12
	s_add_i32 s6, s6, s10
	s_ashr_i32 s10, s6, 31
	s_lshr_b32 s10, s10, 26
	s_add_i32 s10, s6, s10
	s_ashr_i32 s11, s10, 6
	s_and_b32 s10, s10, 0xffc0
	s_sub_i32 s10, s6, s10
	s_bfe_i32 s6, s10, 0x80000
	s_bfe_u32 s6, s6, 0x3000c
	s_add_i32 s12, s10, s6
	s_bfe_i32 s6, s12, 0x80000
	s_and_b32 s12, s12, 0xf8
	s_sub_i32 s10, s10, s12
	s_lshl_b32 s11, s11, 3
	s_sext_i32_i8 s10, s10
	s_add_i32 s22, s11, s10
	s_sext_i32_i16 s6, s6
	s_ashr_i32 s23, s22, 31
	s_lshr_b32 s6, s6, 3
	s_lshl_b64 s[10:11], s[22:23], 20
	s_add_u32 s34, s48, s10
	s_addc_u32 s35, s49, s11
	s_bfe_i64 s[10:11], s[6:7], 0x100000
	s_lshl_b64 s[10:11], s[10:11], 20
	s_add_u32 s36, s50, s10
	s_addc_u32 s37, s51, s11
	s_add_i32 s23, s52, 0
	s_add_i32 m0, s23, 0x10000
	v_lshl_or_b32 v134, v0, 12, v1
	global_load_lds_dwordx4 v130, s[36:37]
	s_add_i32 m0, s23, 0x12000
	v_lshl_or_b32 v128, v4, 12, v1
	global_load_lds_dwordx4 v134, s[36:37]
	s_mov_b32 m0, s23
	s_add_i32 s54, s23, 0x2000
	v_lshl_or_b32 v132, v3, 12, v1
	global_load_lds_dwordx4 v128, s[34:35]
	s_mov_b32 m0, s54
	s_add_u32 s10, s36, 0x80000
	global_load_lds_dwordx4 v132, s[34:35]
	s_addc_u32 s11, s37, 0
	s_add_i32 m0, s23, 0x14000
	v_mov_b32_e32 v131, 0
	global_load_lds_dwordx4 v130, s[10:11]
	s_add_i32 m0, s23, 0x16000
	v_mov_b32_e32 v135, v131
	global_load_lds_dwordx4 v134, s[10:11]
	s_add_u32 s10, s34, 0x80000
	s_addc_u32 s11, s35, 0
	s_add_i32 s55, s23, 0x4000
	s_mov_b32 m0, s55
	s_add_i32 s56, s23, 0x6000
	global_load_lds_dwordx4 v128, s[10:11]
	s_mov_b32 m0, s56
	v_mov_b32_e32 v129, v131
	global_load_lds_dwordx4 v132, s[10:11]
	v_mov_b32_e32 v133, v131
	s_mov_b32 s57, 0
	v_lshl_add_u64 v[6:7], s[36:37], 0, v[130:131]
	v_lshl_add_u64 v[4:5], s[36:37], 0, v[134:135]
	v_lshl_add_u64 v[2:3], s[34:35], 0, v[128:129]
	v_lshl_add_u64 v[0:1], s[34:35], 0, v[132:133]
	s_cmp_lg_u32 s7, 1
	s_mov_b64 s[10:11], 0x80000
	s_cbranch_scc1 .LBB0_1421
	s_barrier

.LBB0_1429:
	ds_read_b128 v[150:153], v147
	ds_read_b128 v[154:157], v147 offset:1024
	ds_read_b128 v[158:161], v147 offset:2048
	ds_read_b128 v[162:165], v147 offset:3072
	s_add_u32 s33, s34, 0xfff80080
	s_addc_u32 s36, s35, -1
	s_cmp_eq_u32 s73, 28
	s_cselect_b32 s39, s27, s36
	s_cselect_b32 s38, s69, s33
	s_cselect_b32 s37, s25, s72
	s_cselect_b32 s36, s70, s71
	v_lshl_add_u64 v[200:201], s[34:35], 0, v[136:137]
	s_add_i32 m0, s23, 0xc000
	ds_read_b128 v[166:169], v148
	ds_read_b128 v[170:173], v148 offset:1024
	ds_read_b128 v[174:177], v148 offset:2048
	ds_read_b128 v[178:181], v148 offset:3072
	ds_read_b128 v[182:185], v148 offset:4096
	ds_read_b128 v[186:189], v148 offset:5120
	ds_read_b128 v[190:193], v148 offset:6144
	ds_read_b128 v[194:197], v148 offset:7168
	global_load_lds_dwordx4 v[200:201], off
	v_lshl_add_u64 v[200:201], s[34:35], 0, v[138:139]
	s_add_i32 m0, s23, 0xe000
	s_nop 0
	global_load_lds_dwordx4 v[200:201], off
	s_waitcnt lgkmcnt(8)
	s_barrier
	s_waitcnt lgkmcnt(0)
	s_setprio 1
	s_waitcnt lgkmcnt(0)
	v_mfma_f32_16x16x32_bf16 v[124:127], v[150:153], v[166:169], v[124:127]
	v_mfma_f32_16x16x32_bf16 v[120:123], v[158:161], v[166:169], v[120:123]
	v_mfma_f32_16x16x32_bf16 v[116:119], v[150:153], v[174:177], v[116:119]
	v_mfma_f32_16x16x32_bf16 v[112:115], v[158:161], v[174:177], v[112:115]
	v_mfma_f32_16x16x32_bf16 v[108:111], v[150:153], v[182:185], v[108:111]
	v_mfma_f32_16x16x32_bf16 v[104:107], v[158:161], v[182:185], v[104:107]
	v_mfma_f32_16x16x32_bf16 v[100:103], v[150:153], v[190:193], v[100:103]
	v_mfma_f32_16x16x32_bf16 v[96:99], v[158:161], v[190:193], v[96:99]
	v_mfma_f32_16x16x32_bf16 v[124:127], v[154:157], v[170:173], v[124:127]
	v_mfma_f32_16x16x32_bf16 v[120:123], v[162:165], v[170:173], v[120:123]
	v_mfma_f32_16x16x32_bf16 v[116:119], v[154:157], v[178:181], v[116:119]
	v_mfma_f32_16x16x32_bf16 v[112:115], v[162:165], v[178:181], v[112:115]
	v_mfma_f32_16x16x32_bf16 v[108:111], v[154:157], v[186:189], v[108:111]
	v_mfma_f32_16x16x32_bf16 v[104:107], v[162:165], v[186:189], v[104:107]
	v_mfma_f32_16x16x32_bf16 v[100:103], v[154:157], v[194:197], v[100:103]
	v_mfma_f32_16x16x32_bf16 v[96:99], v[162:165], v[194:197], v[96:99]
	s_setprio 0
	s_barrier
	s_add_i32 s33, s62, s52
	v_lshl_add_u64 v[218:219], s[36:37], 0, v[130:131]
	s_mov_b32 m0, s33
	ds_read_b128 v[200:203], v149
	ds_read_b128 v[204:207], v149 offset:1024
	ds_read_b128 v[208:211], v149 offset:2048
	ds_read_b128 v[214:217], v149 offset:3072
	global_load_lds_dwordx4 v[218:219], off
	v_lshl_add_u64 v[220:221], s[36:37], 0, v[134:135]
	s_add_i32 m0, s33, 0x2000
	s_nop 0
	global_load_lds_dwordx4 v[220:221], off
	s_barrier
	s_waitcnt lgkmcnt(0)
	s_setprio 1
	s_waitcnt lgkmcnt(0)
	v_mfma_f32_16x16x32_bf16 v[80:83], v[200:203], v[166:169], v[80:83]
	v_mfma_f32_16x16x32_bf16 v[72:75], v[208:211], v[166:169], v[72:75]
	v_mfma_f32_16x16x32_bf16 v[68:71], v[200:203], v[174:177], v[68:71]
	v_mfma_f32_16x16x32_bf16 v[60:63], v[208:211], v[174:177], v[60:63]
	v_mfma_f32_16x16x32_bf16 v[52:55], v[200:203], v[182:185], v[52:55]
	v_mfma_f32_16x16x32_bf16 v[48:51], v[208:211], v[182:185], v[48:51]
	v_mfma_f32_16x16x32_bf16 v[36:39], v[200:203], v[190:193], v[36:39]
	v_mfma_f32_16x16x32_bf16 v[32:35], v[208:211], v[190:193], v[32:35]
	v_mfma_f32_16x16x32_bf16 v[80:83], v[204:207], v[170:173], v[80:83]
	v_mfma_f32_16x16x32_bf16 v[72:75], v[214:217], v[170:173], v[72:75]
	v_mfma_f32_16x16x32_bf16 v[68:71], v[204:207], v[178:181], v[68:71]
	v_mfma_f32_16x16x32_bf16 v[60:63], v[214:217], v[178:181], v[60:63]
	v_mfma_f32_16x16x32_bf16 v[52:55], v[204:207], v[186:189], v[52:55]
	v_mfma_f32_16x16x32_bf16 v[48:51], v[214:217], v[186:189], v[48:51]
	v_mfma_f32_16x16x32_bf16 v[36:39], v[204:207], v[194:197], v[36:39]
	v_mfma_f32_16x16x32_bf16 v[32:35], v[214:217], v[194:197], v[32:35]
	s_setprio 0
	s_mov_b32 m0, s23
	v_lshl_add_u64 v[222:223], s[38:39], 0, v[128:129]
	s_barrier
	ds_read_b128 v[166:169], v148 offset:16384
	ds_read_b128 v[170:173], v148 offset:17408
	ds_read_b128 v[174:177], v148 offset:18432
	ds_read_b128 v[178:181], v148 offset:19456
	ds_read_b128 v[182:185], v148 offset:20480
	ds_read_b128 v[186:189], v148 offset:21504
	ds_read_b128 v[190:193], v148 offset:22528
	ds_read_b128 v[194:197], v148 offset:23552
	global_load_lds_dwordx4 v[222:223], off
	v_lshl_add_u64 v[224:225], s[38:39], 0, v[132:133]
	s_mov_b32 m0, s54
	s_nop 0
	global_load_lds_dwordx4 v[224:225], off
	s_barrier
	s_waitcnt lgkmcnt(0)
	s_setprio 1
	s_waitcnt lgkmcnt(0)
	v_mfma_f32_16x16x32_bf16 v[92:95], v[150:153], v[166:169], v[92:95]
	v_mfma_f32_16x16x32_bf16 v[88:91], v[158:161], v[166:169], v[88:91]
	v_mfma_f32_16x16x32_bf16 v[84:87], v[150:153], v[174:177], v[84:87]
	v_mfma_f32_16x16x32_bf16 v[76:79], v[158:161], v[174:177], v[76:79]
	v_mfma_f32_16x16x32_bf16 v[64:67], v[150:153], v[182:185], v[64:67]
	v_mfma_f32_16x16x32_bf16 v[56:59], v[158:161], v[182:185], v[56:59]
	v_mfma_f32_16x16x32_bf16 v[44:47], v[150:153], v[190:193], v[44:47]
	v_mfma_f32_16x16x32_bf16 v[40:43], v[158:161], v[190:193], v[40:43]
	v_mfma_f32_16x16x32_bf16 v[92:95], v[154:157], v[170:173], v[92:95]
	v_mfma_f32_16x16x32_bf16 v[88:91], v[162:165], v[170:173], v[88:91]
	v_mfma_f32_16x16x32_bf16 v[84:87], v[154:157], v[178:181], v[84:87]
	v_mfma_f32_16x16x32_bf16 v[76:79], v[162:165], v[178:181], v[76:79]
	v_mfma_f32_16x16x32_bf16 v[64:67], v[154:157], v[186:189], v[64:67]
	v_mfma_f32_16x16x32_bf16 v[56:59], v[162:165], v[186:189], v[56:59]
	v_mfma_f32_16x16x32_bf16 v[44:47], v[154:157], v[194:197], v[44:47]
	v_mfma_f32_16x16x32_bf16 v[40:43], v[162:165], v[194:197], v[40:43]
	s_setprio 0
	s_barrier
	s_add_u32 s74, s36, 0x80000
	s_addc_u32 s75, s37, 0
	s_add_i32 s33, s63, s52
	v_lshl_add_u64 v[150:151], s[74:75], 0, v[130:131]
	s_mov_b32 m0, s33
	s_nop 0
	global_load_lds_dwordx4 v[150:151], off
	v_lshl_add_u64 v[150:151], s[74:75], 0, v[134:135]
	s_add_i32 m0, s33, 0x2000
	s_nop 0
	global_load_lds_dwordx4 v[150:151], off
	s_cmp_lg_u32 s73, -2
	s_cbranch_scc1 .Lgh_p11_strict
	s_cmp_eq_u32 s99, 0
	s_cbranch_scc1 .Lgh_p11_strict
	s_waitcnt vmcnt(24)
	s_branch .Lgh_p11_join

.Lgh_p11_join:
	s_barrier
	s_setprio 1
	v_mfma_f32_16x16x32_bf16 v[28:31], v[200:203], v[166:169], v[28:31]
	v_mfma_f32_16x16x32_bf16 v[24:27], v[208:211], v[166:169], v[24:27]
	v_mfma_f32_16x16x32_bf16 v[20:23], v[200:203], v[174:177], v[20:23]
	v_mfma_f32_16x16x32_bf16 v[16:19], v[208:211], v[174:177], v[16:19]
	v_mfma_f32_16x16x32_bf16 v[12:15], v[200:203], v[182:185], v[12:15]
	v_mfma_f32_16x16x32_bf16 v[8:11], v[208:211], v[182:185], v[8:11]
	v_mfma_f32_16x16x32_bf16 v[4:7], v[200:203], v[190:193], v[4:7]
	v_mfma_f32_16x16x32_bf16 v[0:3], v[208:211], v[190:193], v[0:3]
	v_mfma_f32_16x16x32_bf16 v[28:31], v[204:207], v[170:173], v[28:31]
	v_mfma_f32_16x16x32_bf16 v[24:27], v[214:217], v[170:173], v[24:27]
	v_mfma_f32_16x16x32_bf16 v[20:23], v[204:207], v[178:181], v[20:23]
	v_mfma_f32_16x16x32_bf16 v[16:19], v[214:217], v[178:181], v[16:19]
	v_mfma_f32_16x16x32_bf16 v[12:15], v[204:207], v[186:189], v[12:15]
	v_mfma_f32_16x16x32_bf16 v[8:11], v[214:217], v[186:189], v[8:11]
	v_mfma_f32_16x16x32_bf16 v[4:7], v[204:207], v[194:197], v[4:7]
	v_mfma_f32_16x16x32_bf16 v[0:3], v[214:217], v[194:197], v[0:3]
	s_setprio 0
	s_add_i32 s33, 0, 0x18000
	v_add_u32_e32 v162, s33, v145
	s_barrier
	ds_read_b128 v[150:153], v162
	ds_read_b128 v[154:157], v162 offset:1024
	ds_read_b128 v[158:161], v162 offset:2048
	ds_read_b128 v[162:165], v162 offset:3072
	s_add_u32 s38, s38, 0x80000
	s_addc_u32 s39, s39, 0
	s_mov_b32 m0, s55
	v_lshl_add_u64 v[200:201], s[38:39], 0, v[128:129]
	ds_read_b128 v[166:169], v148 offset:32768
	ds_read_b128 v[170:173], v148 offset:33792
	ds_read_b128 v[174:177], v148 offset:34816
	ds_read_b128 v[178:181], v148 offset:35840
	ds_read_b128 v[182:185], v148 offset:36864
	ds_read_b128 v[186:189], v148 offset:37888
	ds_read_b128 v[190:193], v148 offset:38912
	ds_read_b128 v[194:197], v148 offset:39936
	global_load_lds_dwordx4 v[200:201], off
	v_lshl_add_u64 v[200:201], s[38:39], 0, v[132:133]
	s_mov_b32 m0, s56
	s_nop 0
	global_load_lds_dwordx4 v[200:201], off
	s_waitcnt lgkmcnt(8)
	s_barrier
	s_waitcnt lgkmcnt(0)
	s_setprio 1
	s_waitcnt lgkmcnt(0)
	v_mfma_f32_16x16x32_bf16 v[124:127], v[150:153], v[166:169], v[124:127]
	v_mfma_f32_16x16x32_bf16 v[120:123], v[158:161], v[166:169], v[120:123]
	v_mfma_f32_16x16x32_bf16 v[116:119], v[150:153], v[174:177], v[116:119]
	v_mfma_f32_16x16x32_bf16 v[112:115], v[158:161], v[174:177], v[112:115]
	v_mfma_f32_16x16x32_bf16 v[108:111], v[150:153], v[182:185], v[108:111]
	v_mfma_f32_16x16x32_bf16 v[104:107], v[158:161], v[182:185], v[104:107]
	v_mfma_f32_16x16x32_bf16 v[100:103], v[150:153], v[190:193], v[100:103]
	v_mfma_f32_16x16x32_bf16 v[96:99], v[158:161], v[190:193], v[96:99]
	v_mfma_f32_16x16x32_bf16 v[124:127], v[154:157], v[170:173], v[124:127]
	v_mfma_f32_16x16x32_bf16 v[120:123], v[162:165], v[170:173], v[120:123]
	v_mfma_f32_16x16x32_bf16 v[116:119], v[154:157], v[178:181], v[116:119]
	v_mfma_f32_16x16x32_bf16 v[112:115], v[162:165], v[178:181], v[112:115]
	v_mfma_f32_16x16x32_bf16 v[108:111], v[154:157], v[186:189], v[108:111]
	v_mfma_f32_16x16x32_bf16 v[104:107], v[162:165], v[186:189], v[104:107]
	v_mfma_f32_16x16x32_bf16 v[100:103], v[154:157], v[194:197], v[100:103]
	v_mfma_f32_16x16x32_bf16 v[96:99], v[162:165], v[194:197], v[96:99]
	s_setprio 0
	s_barrier
	s_add_i32 s38, 0, 0x1c000
	s_add_i32 s33, s33, s52
	v_add_u32_e32 v199, s38, v145
	v_lshl_add_u64 v[218:219], v[218:219], 0, s[14:15]
	s_mov_b32 m0, s33
	ds_read_b128 v[200:203], v199
	ds_read_b128 v[204:207], v199 offset:1024
	ds_read_b128 v[208:211], v199 offset:2048
	ds_read_b128 v[214:217], v199 offset:3072
	global_load_lds_dwordx4 v[218:219], off
	v_lshl_add_u64 v[218:219], v[220:221], 0, s[14:15]
	s_add_i32 m0, s33, 0x2000
	s_nop 0
	global_load_lds_dwordx4 v[218:219], off
	s_barrier
	s_waitcnt lgkmcnt(0)
	s_setprio 1
	s_waitcnt lgkmcnt(0)
	v_mfma_f32_16x16x32_bf16 v[80:83], v[200:203], v[166:169], v[80:83]
	v_mfma_f32_16x16x32_bf16 v[72:75], v[208:211], v[166:169], v[72:75]
	v_mfma_f32_16x16x32_bf16 v[68:71], v[200:203], v[174:177], v[68:71]
	v_mfma_f32_16x16x32_bf16 v[60:63], v[208:211], v[174:177], v[60:63]
	v_mfma_f32_16x16x32_bf16 v[52:55], v[200:203], v[182:185], v[52:55]
	v_mfma_f32_16x16x32_bf16 v[48:51], v[208:211], v[182:185], v[48:51]
	v_mfma_f32_16x16x32_bf16 v[36:39], v[200:203], v[190:193], v[36:39]
	v_mfma_f32_16x16x32_bf16 v[32:35], v[208:211], v[190:193], v[32:35]
	v_mfma_f32_16x16x32_bf16 v[80:83], v[204:207], v[170:173], v[80:83]
	v_mfma_f32_16x16x32_bf16 v[72:75], v[214:217], v[170:173], v[72:75]
	v_mfma_f32_16x16x32_bf16 v[68:71], v[204:207], v[178:181], v[68:71]
	v_mfma_f32_16x16x32_bf16 v[60:63], v[214:217], v[178:181], v[60:63]
	v_mfma_f32_16x16x32_bf16 v[52:55], v[204:207], v[186:189], v[52:55]
	v_mfma_f32_16x16x32_bf16 v[48:51], v[214:217], v[186:189], v[48:51]
	v_mfma_f32_16x16x32_bf16 v[36:39], v[204:207], v[194:197], v[36:39]
	v_mfma_f32_16x16x32_bf16 v[32:35], v[214:217], v[194:197], v[32:35]
	s_setprio 0
	s_mov_b32 m0, s59
	v_lshl_add_u64 v[218:219], v[222:223], 0, s[14:15]
	s_barrier
	ds_read_b128 v[166:169], v148 offset:49152
	ds_read_b128 v[170:173], v148 offset:50176
	ds_read_b128 v[174:177], v148 offset:51200
	ds_read_b128 v[178:181], v148 offset:52224
	ds_read_b128 v[182:185], v148 offset:53248
	ds_read_b128 v[186:189], v148 offset:54272
	ds_read_b128 v[190:193], v148 offset:55296
	ds_read_b128 v[194:197], v148 offset:56320
	global_load_lds_dwordx4 v[218:219], off
	v_lshl_add_u64 v[218:219], v[224:225], 0, s[14:15]
	s_mov_b32 m0, s60
	s_nop 0
	global_load_lds_dwordx4 v[218:219], off
	s_barrier
	s_waitcnt lgkmcnt(0)
	s_setprio 1
	s_waitcnt lgkmcnt(0)
	v_mfma_f32_16x16x32_bf16 v[92:95], v[150:153], v[166:169], v[92:95]
	v_mfma_f32_16x16x32_bf16 v[88:91], v[158:161], v[166:169], v[88:91]
	v_mfma_f32_16x16x32_bf16 v[84:87], v[150:153], v[174:177], v[84:87]
	v_mfma_f32_16x16x32_bf16 v[76:79], v[158:161], v[174:177], v[76:79]
	v_mfma_f32_16x16x32_bf16 v[64:67], v[150:153], v[182:185], v[64:67]
	v_mfma_f32_16x16x32_bf16 v[56:59], v[158:161], v[182:185], v[56:59]
	v_mfma_f32_16x16x32_bf16 v[44:47], v[150:153], v[190:193], v[44:47]
	v_mfma_f32_16x16x32_bf16 v[40:43], v[158:161], v[190:193], v[40:43]
	v_mfma_f32_16x16x32_bf16 v[92:95], v[154:157], v[170:173], v[92:95]
	v_mfma_f32_16x16x32_bf16 v[88:91], v[162:165], v[170:173], v[88:91]
	v_mfma_f32_16x16x32_bf16 v[84:87], v[154:157], v[178:181], v[84:87]
	v_mfma_f32_16x16x32_bf16 v[76:79], v[162:165], v[178:181], v[76:79]
	v_mfma_f32_16x16x32_bf16 v[64:67], v[154:157], v[186:189], v[64:67]
	v_mfma_f32_16x16x32_bf16 v[56:59], v[162:165], v[186:189], v[56:59]
	v_mfma_f32_16x16x32_bf16 v[44:47], v[154:157], v[194:197], v[44:47]
	v_mfma_f32_16x16x32_bf16 v[40:43], v[162:165], v[194:197], v[40:43]
	s_setprio 0
	s_barrier
	s_add_u32 s36, s36, 0x80080
	s_addc_u32 s37, s37, 0
	s_add_i32 s33, s38, s52
	v_lshl_add_u64 v[150:151], s[36:37], 0, v[130:131]
	s_mov_b32 m0, s33
	s_nop 0
	global_load_lds_dwordx4 v[150:151], off
	v_lshl_add_u64 v[150:151], s[36:37], 0, v[134:135]
	s_add_i32 m0, s33, 0x2000
	s_nop 0
	global_load_lds_dwordx4 v[150:151], off
	s_waitcnt vmcnt(6)
	s_barrier
	s_setprio 1
	v_mfma_f32_16x16x32_bf16 v[28:31], v[200:203], v[166:169], v[28:31]
	v_mfma_f32_16x16x32_bf16 v[24:27], v[208:211], v[166:169], v[24:27]
	v_mfma_f32_16x16x32_bf16 v[20:23], v[200:203], v[174:177], v[20:23]
	v_mfma_f32_16x16x32_bf16 v[16:19], v[208:211], v[174:177], v[16:19]
	v_mfma_f32_16x16x32_bf16 v[12:15], v[200:203], v[182:185], v[12:15]
	v_mfma_f32_16x16x32_bf16 v[8:11], v[208:211], v[182:185], v[8:11]
	v_mfma_f32_16x16x32_bf16 v[4:7], v[200:203], v[190:193], v[4:7]
	v_mfma_f32_16x16x32_bf16 v[0:3], v[208:211], v[190:193], v[0:3]
	v_mfma_f32_16x16x32_bf16 v[28:31], v[204:207], v[170:173], v[28:31]
	v_mfma_f32_16x16x32_bf16 v[24:27], v[214:217], v[170:173], v[24:27]
	v_mfma_f32_16x16x32_bf16 v[20:23], v[204:207], v[178:181], v[20:23]
	v_mfma_f32_16x16x32_bf16 v[16:19], v[214:217], v[178:181], v[16:19]
	v_mfma_f32_16x16x32_bf16 v[12:15], v[204:207], v[186:189], v[12:15]
	v_mfma_f32_16x16x32_bf16 v[8:11], v[214:217], v[186:189], v[8:11]
	v_mfma_f32_16x16x32_bf16 v[4:7], v[204:207], v[194:197], v[4:7]
	v_mfma_f32_16x16x32_bf16 v[0:3], v[214:217], v[194:197], v[0:3]
	s_setprio 0
	s_add_i32 s73, s73, 2
	s_add_u32 s34, s34, 0x100
	s_addc_u32 s35, s35, 0
	s_add_u32 s71, s71, 0x100
	s_addc_u32 s72, s72, 0
	s_cmp_gt_u32 s73, 29
	s_barrier
	s_cbranch_scc0 .LBB0_1429
	s_add_u32 s100, s69, 0x80080
	s_addc_u32 s101, s27, 0
	s_mov_b32 s99, 1
	v_lshl_add_u64 v[200:201], s[100:101], 0, v[136:137]
	s_add_i32 m0, s23, 0xc000
	s_nop 0
	global_load_lds_dwordx4 v[200:201], off
	v_lshl_add_u64 v[200:201], s[100:101], 0, v[138:139]
	s_add_i32 m0, s23, 0xe000
	s_nop 0
	global_load_lds_dwordx4 v[200:201], off
	v_lshl_add_u32 v150, s22, 8, v144
	v_lshl_or_b32 v152, s68, 8, v146
	v_ashrrev_i32_e32 v151, 31, v150
	v_ashrrev_i32_e32 v153, 31, v152
	v_cvt_pk_bf16_f32 v124, v124, v125
	v_cvt_pk_bf16_f32 v125, v126, v127
	v_cvt_pk_bf16_f32 v126, v120, v121
	v_lshlrev_b64 v[120:121], 12, v[150:151]
	v_cvt_pk_bf16_f32 v127, v122, v123
	v_lshl_add_u64 v[120:121], s[12:13], 0, v[120:121]
	v_lshlrev_b64 v[122:123], 1, v[152:153]
	v_lshl_add_u64 v[120:121], v[120:121], 0, v[122:123]
	v_cvt_pk_bf16_f32 v92, v92, v93
	v_cvt_pk_bf16_f32 v93, v94, v95
	v_cvt_pk_bf16_f32 v95, v90, v91
	v_add_co_u32_e32 v90, vcc, s64, v120
	v_cvt_pk_bf16_f32 v84, v84, v85
	s_nop 0
	v_addc_co_u32_e32 v91, vcc, 0, v121, vcc
	v_cvt_pk_bf16_f32 v85, v86, v87
	v_cvt_pk_bf16_f32 v87, v78, v79
	v_add_co_u32_e32 v78, vcc, s65, v120
	v_cvt_pk_bf16_f32 v64, v64, v65
	s_nop 0
	v_addc_co_u32_e32 v79, vcc, 0, v121, vcc
	v_cvt_pk_bf16_f32 v65, v66, v67
	v_cvt_pk_bf16_f32 v67, v58, v59
	v_add_co_u32_e32 v58, vcc, s66, v120
	global_store_dwordx4 v[120:121], v[124:127], off sc1
	s_nop 0
	v_addc_co_u32_e32 v59, vcc, 0, v121, vcc
	v_or_b32_e32 v124, 16, v150
	v_cvt_pk_bf16_f32 v116, v116, v117
	v_cvt_pk_bf16_f32 v117, v118, v119
	v_cvt_pk_bf16_f32 v119, v114, v115
	v_ashrrev_i32_e32 v125, 31, v124
	v_or_b32_e32 v114, 32, v150
	v_cvt_pk_bf16_f32 v108, v108, v109
	v_cvt_pk_bf16_f32 v109, v110, v111
	v_cvt_pk_bf16_f32 v111, v106, v107
	v_or_b32_e32 v106, 48, v150
	v_cvt_pk_bf16_f32 v44, v44, v45
	v_cvt_pk_bf16_f32 v45, v46, v47
	v_cvt_pk_bf16_f32 v46, v40, v41
	v_add_co_u32_e32 v40, vcc, s67, v120
	v_cvt_pk_bf16_f32 v118, v112, v113
	v_lshlrev_b64 v[112:113], 12, v[124:125]
	v_ashrrev_i32_e32 v115, 31, v114
	v_ashrrev_i32_e32 v107, 31, v106
	v_cvt_pk_bf16_f32 v47, v42, v43
	v_addc_co_u32_e32 v41, vcc, 0, v121, vcc
	v_lshl_add_u64 v[112:113], s[12:13], 0, v[112:113]
	v_cvt_pk_bf16_f32 v110, v104, v105
	v_lshlrev_b64 v[104:105], 12, v[114:115]
	v_cvt_pk_bf16_f32 v100, v100, v101
	v_cvt_pk_bf16_f32 v101, v102, v103
	v_cvt_pk_bf16_f32 v102, v96, v97
	v_lshlrev_b64 v[96:97], 12, v[106:107]
	global_store_dwordx4 v[40:41], v[44:47], off sc1
	v_cvt_pk_bf16_f32 v40, v80, v81
	v_cvt_pk_bf16_f32 v41, v82, v83
	v_cvt_pk_bf16_f32 v42, v72, v73
	v_cvt_pk_bf16_f32 v43, v74, v75
	v_lshl_add_u64 v[112:113], v[112:113], 0, v[122:123]
	v_lshl_add_u64 v[104:105], s[12:13], 0, v[104:105]
	v_lshl_add_u64 v[96:97], s[12:13], 0, v[96:97]
	v_cvt_pk_bf16_f32 v66, v56, v57
	global_store_dwordx4 v[120:121], v[40:43], off offset:256 sc1
	v_lshl_add_u64 v[104:105], v[104:105], 0, v[122:123]
	v_cvt_pk_bf16_f32 v103, v98, v99
	v_cvt_pk_bf16_f32 v40, v68, v69
	v_cvt_pk_bf16_f32 v41, v70, v71
	v_cvt_pk_bf16_f32 v42, v60, v61
	v_cvt_pk_bf16_f32 v43, v62, v63
	v_lshl_add_u64 v[96:97], v[96:97], 0, v[122:123]
	v_cvt_pk_bf16_f32 v94, v88, v89
	v_lshl_add_u64 v[88:89], v[120:121], 0, s[10:11]
	v_cvt_pk_bf16_f32 v86, v76, v77
	v_lshl_add_u64 v[76:77], v[120:121], 0, s[16:17]
	v_lshl_add_u64 v[56:57], v[120:121], 0, s[18:19]
	global_store_dwordx4 v[58:59], v[64:67], off sc1
	v_lshl_add_u64 v[58:59], v[120:121], 0, s[20:21]
	global_store_dwordx4 v[112:113], v[40:43], off offset:256 sc1
	v_cvt_pk_bf16_f32 v36, v36, v37
	v_cvt_pk_bf16_f32 v37, v38, v39
	v_cvt_pk_bf16_f32 v40, v52, v53
	v_cvt_pk_bf16_f32 v41, v54, v55
	v_cvt_pk_bf16_f32 v42, v48, v49
	v_cvt_pk_bf16_f32 v43, v50, v51
	v_cvt_pk_bf16_f32 v38, v32, v33
	v_cvt_pk_bf16_f32 v39, v34, v35
	v_cvt_pk_bf16_f32 v28, v28, v29
	v_cvt_pk_bf16_f32 v29, v30, v31
	v_cvt_pk_bf16_f32 v30, v24, v25
	v_cvt_pk_bf16_f32 v31, v26, v27
	v_cvt_pk_bf16_f32 v20, v20, v21
	v_cvt_pk_bf16_f32 v21, v22, v23
	v_cvt_pk_bf16_f32 v22, v16, v17
	v_cvt_pk_bf16_f32 v23, v18, v19
	v_cvt_pk_bf16_f32 v12, v12, v13
	v_cvt_pk_bf16_f32 v13, v14, v15
	v_cvt_pk_bf16_f32 v14, v8, v9
	v_cvt_pk_bf16_f32 v15, v10, v11
	v_cvt_pk_bf16_f32 v4, v4, v5
	v_cvt_pk_bf16_f32 v5, v6, v7
	v_cvt_pk_bf16_f32 v6, v0, v1
	v_cvt_pk_bf16_f32 v7, v2, v3
	s_and_b64 vcc, exec, s[6:7]
	s_mov_b32 s22, s26
	s_mov_b32 s68, s24
	s_mov_b64 s[36:37], s[30:31]
	s_mov_b64 s[34:35], s[28:29]
	global_store_dwordx4 v[112:113], v[116:119], off sc1
	global_store_dwordx4 v[104:105], v[108:111], off sc1
	global_store_dwordx4 v[96:97], v[100:103], off sc1
	global_store_dwordx4 v[90:91], v[92:95], off sc1
	global_store_dwordx4 v[78:79], v[84:87], off sc1
	global_store_dwordx4 v[104:105], v[40:43], off offset:256 sc1
	global_store_dwordx4 v[96:97], v[36:39], off offset:256 sc1
	global_store_dwordx4 v[88:89], v[28:31], off offset:256 sc1
	global_store_dwordx4 v[76:77], v[20:23], off offset:256 sc1
	global_store_dwordx4 v[56:57], v[12:15], off offset:256 sc1
	global_store_dwordx4 v[58:59], v[4:7], off offset:256 sc1
	s_cbranch_vccz .LBB0_1422
	s_waitcnt vmcnt(0)
	s_cmpk_gt_u32 s3, 0xff
	s_cbranch_scc1 .LBB0_1433
	s_barrier

	.amdhsa_kernel _Z8yoco_fwd4Args
		.amdhsa_group_segment_fixed_size 0
		.amdhsa_private_segment_fixed_size 0
		.amdhsa_kernarg_size 480
		.amdhsa_user_sgpr_count 2
		.amdhsa_user_sgpr_dispatch_ptr 0
		.amdhsa_user_sgpr_queue_ptr 0
		.amdhsa_user_sgpr_kernarg_segment_ptr 1
		.amdhsa_user_sgpr_dispatch_id 0
		.amdhsa_user_sgpr_kernarg_preload_length 0
		.amdhsa_user_sgpr_kernarg_preload_offset 0
		.amdhsa_user_sgpr_private_segment_size 0
		.amdhsa_uses_dynamic_stack 0
		.amdhsa_enable_private_segment 0
		.amdhsa_system_sgpr_workgroup_id_x 1
		.amdhsa_system_sgpr_workgroup_id_y 0
		.amdhsa_system_sgpr_workgroup_id_z 0
		.amdhsa_system_sgpr_workgroup_info 0
		.amdhsa_system_vgpr_workitem_id 2
		.amdhsa_next_free_vgpr 253
		.amdhsa_next_free_sgpr 102
		.amdhsa_accum_offset 256
		.amdhsa_reserve_vcc 1
		.amdhsa_float_round_mode_32 0
		.amdhsa_float_round_mode_16_64 0
		.amdhsa_float_denorm_mode_32 3
		.amdhsa_float_denorm_mode_16_64 3
		.amdhsa_dx10_clamp 1
		.amdhsa_ieee_mode 1
		.amdhsa_fp16_overflow 0
		.amdhsa_tg_split 0
		.amdhsa_exception_fp_ieee_invalid_op 0
		.amdhsa_exception_fp_denorm_src 0
		.amdhsa_exception_fp_ieee_div_zero 0
		.amdhsa_exception_fp_ieee_overflow 0
		.amdhsa_exception_fp_ieee_underflow 0
		.amdhsa_exception_fp_ieee_inexact 0
		.amdhsa_exception_int_div_zero 0
	.end_amdhsa_kernel

amdhsa.kernels:
  - .agpr_count:     0
    .args:
      - .offset:         0
        .size:           224
        .value_kind:     by_value
      - .offset:         224
        .size:           4
        .value_kind:     hidden_block_count_x
      - .offset:         228
        .size:           4
        .value_kind:     hidden_block_count_y
      - .offset:         232
        .size:           4
        .value_kind:     hidden_block_count_z
      - .offset:         236
        .size:           2
        .value_kind:     hidden_group_size_x
      - .offset:         238
        .size:           2
        .value_kind:     hidden_group_size_y
      - .offset:         240
        .size:           2
        .value_kind:     hidden_group_size_z
      - .offset:         242
        .size:           2
        .value_kind:     hidden_remainder_x
      - .offset:         244
        .size:           2
        .value_kind:     hidden_remainder_y
      - .offset:         246
        .size:           2
        .value_kind:     hidden_remainder_z
      - .offset:         264
        .size:           8
        .value_kind:     hidden_global_offset_x
      - .offset:         272
        .size:           8
        .value_kind:     hidden_global_offset_y
      - .offset:         280
        .size:           8
        .value_kind:     hidden_global_offset_z
      - .offset:         288
        .size:           2
        .value_kind:     hidden_grid_dims
      - .offset:         312
        .size:           8
        .value_kind:     hidden_multigrid_sync_arg
      - .offset:         344
        .size:           4
        .value_kind:     hidden_dynamic_lds_size
    .group_segment_fixed_size: 0
    .kernarg_segment_align: 8
    .kernarg_segment_size: 480
    .language:       OpenCL C
    .language_version:
      - 2
      - 0
    .max_flat_workgroup_size: 512
    .name:           _Z8yoco_fwd4Args
    .private_segment_fixed_size: 0
    .sgpr_count:     108
    .sgpr_spill_count: 10
    .symbol:         _Z8yoco_fwd4Args.kd
    .uniform_work_group_size: 1
    .uses_dynamic_stack: false
    .vgpr_count:     253
    .vgpr_spill_count: 0
    .wavefront_size: 64
